# v25 + nt hint also on the prologue's bf16 weight-copy stores
# baseline (speedup 1.0000x reference)
.LBB0_22:
	s_lshl_b32 s56, s16, 1
	s_lshl_b32 s57, s9, 1
	v_add_u32_e32 v48, s56, v2
	v_add_u32_e32 v50, s57, v19
	v_add_u32_e32 v52, s56, v26
	v_add_u32_e32 v54, s57, v21
	v_add_u32_e32 v56, s56, v28
	v_add_u32_e32 v58, s57, v23
	v_add_u32_e32 v60, s56, v30
	v_add_u32_e32 v62, s57, v27
	v_add_u32_e32 v64, s56, v32
	v_add_u32_e32 v66, s57, v29
	v_add_u32_e32 v68, s56, v34
	v_add_u32_e32 v70, s57, v31
	v_add_u32_e32 v72, s56, v36
	v_add_u32_e32 v74, s57, v33
	v_add_u32_e32 v76, s56, v38
	v_add_u32_e32 v78, s57, v35
	v_ashrrev_i32_e32 v49, 31, v48
	v_ashrrev_i32_e32 v51, 31, v50
	v_ashrrev_i32_e32 v53, 31, v52
	v_ashrrev_i32_e32 v55, 31, v54
	v_ashrrev_i32_e32 v57, 31, v56
	v_ashrrev_i32_e32 v59, 31, v58
	v_ashrrev_i32_e32 v61, 31, v60
	v_ashrrev_i32_e32 v63, 31, v62
	v_ashrrev_i32_e32 v65, 31, v64
	v_ashrrev_i32_e32 v67, 31, v66
	v_ashrrev_i32_e32 v69, 31, v68
	v_ashrrev_i32_e32 v71, 31, v70
	v_ashrrev_i32_e32 v73, 31, v72
	v_ashrrev_i32_e32 v75, 31, v74
	v_ashrrev_i32_e32 v77, 31, v76
	v_ashrrev_i32_e32 v79, 31, v78
	v_lshlrev_b64 v[48:49], 12, v[48:49]
	v_lshlrev_b64 v[50:51], 12, v[50:51]
	v_lshlrev_b64 v[52:53], 12, v[52:53]
	v_lshlrev_b64 v[54:55], 12, v[54:55]
	v_lshlrev_b64 v[56:57], 12, v[56:57]
	v_lshlrev_b64 v[58:59], 12, v[58:59]
	v_lshlrev_b64 v[60:61], 12, v[60:61]
	v_lshlrev_b64 v[62:63], 12, v[62:63]
	v_lshlrev_b64 v[64:65], 12, v[64:65]
	v_lshlrev_b64 v[66:67], 12, v[66:67]
	v_lshlrev_b64 v[68:69], 12, v[68:69]
	v_lshlrev_b64 v[70:71], 12, v[70:71]
	v_lshlrev_b64 v[72:73], 12, v[72:73]
	v_lshlrev_b64 v[74:75], 12, v[74:75]
	v_lshlrev_b64 v[76:77], 12, v[76:77]
	v_lshlrev_b64 v[78:79], 12, v[78:79]
	v_lshl_add_u64 v[48:49], v[24:25], 0, v[48:49]
	v_lshl_add_u64 v[50:51], v[24:25], 0, v[50:51]
	v_lshl_add_u64 v[52:53], v[24:25], 0, v[52:53]
	v_lshl_add_u64 v[54:55], v[24:25], 0, v[54:55]
	v_lshl_add_u64 v[56:57], v[24:25], 0, v[56:57]
	v_lshl_add_u64 v[58:59], v[24:25], 0, v[58:59]
	v_lshl_add_u64 v[60:61], v[24:25], 0, v[60:61]
	v_lshl_add_u64 v[62:63], v[24:25], 0, v[62:63]
	v_lshl_add_u64 v[64:65], v[24:25], 0, v[64:65]
	v_lshl_add_u64 v[66:67], v[24:25], 0, v[66:67]
	v_lshl_add_u64 v[68:69], v[24:25], 0, v[68:69]
	v_lshl_add_u64 v[70:71], v[24:25], 0, v[70:71]
	v_lshl_add_u64 v[72:73], v[24:25], 0, v[72:73]
	v_lshl_add_u64 v[74:75], v[24:25], 0, v[74:75]
	v_lshl_add_u64 v[76:77], v[24:25], 0, v[76:77]
	v_lshl_add_u64 v[78:79], v[24:25], 0, v[78:79]
	global_load_dword v37, v[48:49], off nt
	global_load_dword v40, v[50:51], off nt
	global_load_dword v47, v[52:53], off nt
	global_load_dword v80, v[54:55], off nt
	global_load_dword v81, v[56:57], off nt
	global_load_dword v82, v[58:59], off nt
	global_load_dword v83, v[60:61], off nt
	global_load_dword v84, v[62:63], off nt
	global_load_dword v85, v[64:65], off nt
	global_load_dword v86, v[66:67], off nt
	global_load_dword v87, v[68:69], off nt
	global_load_dword v88, v[70:71], off nt
	global_load_dword v89, v[72:73], off nt
	global_load_dword v90, v[74:75], off nt
	global_load_dword v91, v[76:77], off nt
	global_load_dword v92, v[78:79], off nt
	s_add_i32 s16, s16, 16
	s_add_i32 s9, s9, 16
	s_add_i32 s17, s17, -16
	v_add_u32_e32 v48, s56, v0
	v_add_u32_e32 v50, s57, v1
	v_add_u32_e32 v52, s56, v8
	v_add_u32_e32 v54, s57, v5
	v_add_u32_e32 v56, s56, v10
	v_add_u32_e32 v58, s57, v7
	v_add_u32_e32 v60, s56, v12
	v_add_u32_e32 v62, s57, v9
	v_add_u32_e32 v64, s56, v14
	v_add_u32_e32 v66, s57, v11
	v_add_u32_e32 v68, s56, v16
	v_add_u32_e32 v70, s57, v13
	v_add_u32_e32 v72, s56, v18
	v_add_u32_e32 v74, s57, v15
	v_add_u32_e32 v76, s56, v20
	v_add_u32_e32 v78, s57, v17
	s_cmp_lg_u32 s17, 0
	v_mad_u64_u32 v[48:49], s[56:57], v48, s35, v[4:5]
	v_mad_u64_u32 v[50:51], s[56:57], v50, s35, v[4:5]
	v_mad_u64_u32 v[52:53], s[56:57], v52, s35, v[4:5]
	v_mad_u64_u32 v[54:55], s[56:57], v54, s35, v[4:5]
	v_mad_u64_u32 v[56:57], s[56:57], v56, s35, v[4:5]
	v_mad_u64_u32 v[58:59], s[56:57], v58, s35, v[4:5]
	v_mad_u64_u32 v[60:61], s[56:57], v60, s35, v[4:5]
	v_mad_u64_u32 v[62:63], s[56:57], v62, s35, v[4:5]
	v_mad_u64_u32 v[64:65], s[56:57], v64, s35, v[4:5]
	v_mad_u64_u32 v[66:67], s[56:57], v66, s35, v[4:5]
	v_mad_u64_u32 v[68:69], s[56:57], v68, s35, v[4:5]
	v_mad_u64_u32 v[70:71], s[56:57], v70, s35, v[4:5]
	v_mad_u64_u32 v[72:73], s[56:57], v72, s35, v[4:5]
	v_mad_u64_u32 v[74:75], s[56:57], v74, s35, v[4:5]
	v_mad_u64_u32 v[76:77], s[56:57], v76, s35, v[4:5]
	v_mad_u64_u32 v[78:79], s[56:57], v78, s35, v[4:5]
	s_waitcnt vmcnt(15)
	ds_write_b32 v48, v37
	s_waitcnt vmcnt(14)
	ds_write_b32 v50, v40
	s_waitcnt vmcnt(13)
	ds_write_b32 v52, v47
	s_waitcnt vmcnt(12)
	ds_write_b32 v54, v80
	s_waitcnt vmcnt(11)
	ds_write_b32 v56, v81
	s_waitcnt vmcnt(10)
	ds_write_b32 v58, v82
	s_waitcnt vmcnt(9)
	ds_write_b32 v60, v83
	s_waitcnt vmcnt(8)
	ds_write_b32 v62, v84
	s_waitcnt vmcnt(7)
	ds_write_b32 v64, v85
	s_waitcnt vmcnt(6)
	ds_write_b32 v66, v86
	s_waitcnt vmcnt(5)
	ds_write_b32 v68, v87
	s_waitcnt vmcnt(4)
	ds_write_b32 v70, v88
	s_waitcnt vmcnt(3)
	ds_write_b32 v72, v89
	s_waitcnt vmcnt(2)
	ds_write_b32 v74, v90
	s_waitcnt vmcnt(1)
	ds_write_b32 v76, v91
	s_waitcnt vmcnt(0)
	ds_write_b32 v78, v92
	s_cbranch_scc1 .LBB0_22
	s_waitcnt lgkmcnt(0)
	s_lshl_b64 s[16:17], s[6:7], 19
	ds_read2_b32 v[28:29], v42 offset1:8
	s_add_u32 s7, s19, s16
	ds_read2_b32 v[32:33], v42 offset0:33 offset1:41
	s_addc_u32 s9, s20, s17
	s_lshl_b32 s8, s8, 1
	s_add_u32 s8, s7, s8
	ds_read2_b32 v[34:35], v42 offset0:66 offset1:74
	s_addc_u32 s9, s9, 0
	v_lshlrev_b32_e32 v2, 1, v6
	ds_read2_b32 v[36:37], v42 offset0:99 offset1:107
	v_lshl_add_u64 v[30:31], s[8:9], 0, v[2:3]
	s_waitcnt lgkmcnt(3)
	v_bfe_u32 v2, v28, 16, 1
	v_add3_u32 v2, v28, v2, s37
	s_waitcnt lgkmcnt(2)
	v_bfe_u32 v19, v32, 16, 1
	ds_read2_b32 v[48:49], v42 offset0:132 offset1:140
	v_lshrrev_b32_e32 v2, 16, v2
	v_add3_u32 v19, v32, v19, s37
	ds_read2_b32 v[50:51], v42 offset0:165 offset1:173
	v_and_or_b32 v24, v19, s38, v2
	s_waitcnt lgkmcnt(3)
	v_bfe_u32 v2, v34, 16, 1
	v_add3_u32 v2, v34, v2, s37
	s_waitcnt lgkmcnt(2)
	v_bfe_u32 v19, v36, 16, 1
	ds_read2_b32 v[52:53], v42 offset0:198 offset1:206
	v_lshrrev_b32_e32 v2, 16, v2
	v_add3_u32 v19, v36, v19, s37
	ds_read2_b32 v[54:55], v42 offset0:231 offset1:239
	v_and_or_b32 v25, v19, s38, v2
	s_waitcnt lgkmcnt(3)
	v_bfe_u32 v2, v48, 16, 1
	v_add3_u32 v2, v48, v2, s37
	s_waitcnt lgkmcnt(2)
	v_bfe_u32 v19, v50, 16, 1
	v_lshrrev_b32_e32 v2, 16, v2
	v_add3_u32 v19, v50, v19, s37
	v_and_or_b32 v26, v19, s38, v2
	s_waitcnt lgkmcnt(1)
	v_bfe_u32 v2, v52, 16, 1
	v_add3_u32 v2, v52, v2, s37
	s_waitcnt lgkmcnt(0)
	v_bfe_u32 v19, v54, 16, 1
	v_lshrrev_b32_e32 v2, 16, v2
	v_add3_u32 v19, v54, v19, s37
	v_add_u32_e32 v56, s2, v41
	v_and_or_b32 v27, v19, s38, v2
	v_ashrrev_i32_e32 v57, 31, v56
	v_bfe_u32 v2, v29, 16, 1
	v_lshlrev_b64 v[56:57], 9, v[56:57]
	v_add3_u32 v2, v29, v2, s37
	v_bfe_u32 v19, v33, 16, 1
	v_lshl_add_u64 v[56:57], v[30:31], 0, v[56:57]
	v_lshrrev_b32_e32 v2, 16, v2
	v_add3_u32 v19, v33, v19, s37
	global_store_dwordx4 v[56:57], v[24:27], off nt
	v_add_u32_e32 v28, s2, v43
	v_ashrrev_i32_e32 v29, 31, v28
	v_and_or_b32 v24, v19, s38, v2
	v_bfe_u32 v2, v35, 16, 1
	v_add3_u32 v2, v35, v2, s37
	v_bfe_u32 v19, v37, 16, 1
	v_lshrrev_b32_e32 v2, 16, v2
	v_add3_u32 v19, v37, v19, s37
	v_and_or_b32 v25, v19, s38, v2
	v_bfe_u32 v2, v49, 16, 1
	v_add3_u32 v2, v49, v2, s37
	v_bfe_u32 v19, v51, 16, 1
	v_lshrrev_b32_e32 v2, 16, v2
	v_add3_u32 v19, v51, v19, s37
	v_and_or_b32 v26, v19, s38, v2
	v_bfe_u32 v2, v53, 16, 1
	v_add3_u32 v2, v53, v2, s37
	v_bfe_u32 v19, v55, 16, 1
	v_lshrrev_b32_e32 v2, 16, v2
	v_add3_u32 v19, v55, v19, s37
	v_lshlrev_b64 v[28:29], 9, v[28:29]
	v_and_or_b32 v27, v19, s38, v2
	ds_read2_b32 v[32:33], v42 offset0:16 offset1:24
	v_lshl_add_u64 v[28:29], v[30:31], 0, v[28:29]
	global_store_dwordx4 v[28:29], v[24:27], off nt
	ds_read2_b32 v[28:29], v42 offset0:49 offset1:57
	ds_read2_b32 v[34:35], v42 offset0:82 offset1:90
	ds_read2_b32 v[36:37], v42 offset0:115 offset1:123
	s_waitcnt lgkmcnt(3)
	v_bfe_u32 v2, v32, 16, 1
	v_add3_u32 v2, v32, v2, s37
	s_waitcnt lgkmcnt(2)
	v_bfe_u32 v19, v28, 16, 1
	ds_read2_b32 v[48:49], v42 offset0:148 offset1:156
	v_lshrrev_b32_e32 v2, 16, v2
	v_add3_u32 v19, v28, v19, s37
	ds_read2_b32 v[50:51], v42 offset0:181 offset1:189
	v_and_or_b32 v24, v19, s38, v2
	s_waitcnt lgkmcnt(3)
	v_bfe_u32 v2, v34, 16, 1
	v_add3_u32 v2, v34, v2, s37
	s_waitcnt lgkmcnt(2)
	v_bfe_u32 v19, v36, 16, 1
	ds_read2_b32 v[52:53], v42 offset0:214 offset1:222
	v_lshrrev_b32_e32 v2, 16, v2
	v_add3_u32 v19, v36, v19, s37
	ds_read2_b32 v[54:55], v42 offset0:247 offset1:255
	v_and_or_b32 v25, v19, s38, v2
	s_waitcnt lgkmcnt(3)
	v_bfe_u32 v2, v48, 16, 1
	v_add3_u32 v2, v48, v2, s37
	s_waitcnt lgkmcnt(2)
	v_bfe_u32 v19, v50, 16, 1
	v_lshrrev_b32_e32 v2, 16, v2
	v_add3_u32 v19, v50, v19, s37
	v_and_or_b32 v26, v19, s38, v2
	s_waitcnt lgkmcnt(1)
	v_bfe_u32 v2, v52, 16, 1
	v_add3_u32 v2, v52, v2, s37
	s_waitcnt lgkmcnt(0)
	v_bfe_u32 v19, v54, 16, 1
	v_lshrrev_b32_e32 v2, 16, v2
	v_add3_u32 v19, v54, v19, s37
	v_add_u32_e32 v56, s2, v44
	v_and_or_b32 v27, v19, s38, v2
	v_ashrrev_i32_e32 v57, 31, v56
	v_bfe_u32 v19, v33, 16, 1
	v_lshlrev_b64 v[56:57], 9, v[56:57]
	v_bfe_u32 v2, v29, 16, 1
	v_add3_u32 v19, v33, v19, s37
	v_lshl_add_u64 v[56:57], v[30:31], 0, v[56:57]
	v_add3_u32 v2, v29, v2, s37
	v_lshrrev_b32_e32 v19, 16, v19
	global_store_dwordx4 v[56:57], v[24:27], off nt
	v_add_u32_e32 v28, s2, v45
	v_ashrrev_i32_e32 v29, 31, v28
	v_and_or_b32 v24, v2, s38, v19
	v_bfe_u32 v19, v35, 16, 1
	v_bfe_u32 v2, v37, 16, 1
	v_add3_u32 v19, v35, v19, s37
	v_add3_u32 v2, v37, v2, s37
	v_lshrrev_b32_e32 v19, 16, v19
	v_and_or_b32 v25, v2, s38, v19
	v_bfe_u32 v19, v49, 16, 1
	v_bfe_u32 v2, v51, 16, 1
	v_add3_u32 v19, v49, v19, s37
	v_add3_u32 v2, v51, v2, s37
	v_lshrrev_b32_e32 v19, 16, v19
	v_and_or_b32 v26, v2, s38, v19
	v_bfe_u32 v19, v53, 16, 1
	v_bfe_u32 v2, v55, 16, 1
	v_add3_u32 v19, v53, v19, s37
	v_add3_u32 v2, v55, v2, s37
	v_lshrrev_b32_e32 v19, 16, v19
	v_lshlrev_b64 v[28:29], 9, v[28:29]
	v_and_or_b32 v27, v2, s38, v19
	v_lshl_add_u64 v[28:29], v[30:31], 0, v[28:29]
	global_store_dwordx4 v[28:29], v[24:27], off nt
	s_waitcnt lgkmcnt(0)
	s_mov_b64 s[8:9], 0

.LBB0_26:
	s_lshl_b32 s17, s9, 1
	s_lshl_b32 s58, s8, 1
	v_add_u32_e32 v37, s17, v2
	v_add_u32_e32 v40, s58, v19
	v_add_u32_e32 v47, s17, v26
	v_add_u32_e32 v54, s58, v21
	v_add_u32_e32 v56, s17, v28
	v_add_u32_e32 v58, s58, v23
	v_add_u32_e32 v60, s17, v30
	v_add_u32_e32 v62, s58, v27
	v_add_u32_e32 v64, s17, v32
	v_add_u32_e32 v66, s58, v29
	v_add_u32_e32 v68, s17, v34
	v_add_u32_e32 v70, s58, v31
	v_add_u32_e32 v72, s17, v36
	v_add_u32_e32 v74, s58, v33
	v_add_u32_e32 v76, s17, v38
	v_add_u32_e32 v78, s58, v35
	v_mad_i64_i32 v[48:49], s[56:57], v37, s40, v[24:25]
	v_mad_i64_i32 v[50:51], s[56:57], v40, s40, v[24:25]
	v_mad_i64_i32 v[52:53], s[56:57], v47, s40, v[24:25]
	v_mad_i64_i32 v[54:55], s[56:57], v54, s40, v[24:25]
	v_mad_i64_i32 v[56:57], s[56:57], v56, s40, v[24:25]
	v_mad_i64_i32 v[58:59], s[56:57], v58, s40, v[24:25]
	v_mad_i64_i32 v[60:61], s[56:57], v60, s40, v[24:25]
	v_mad_i64_i32 v[62:63], s[56:57], v62, s40, v[24:25]
	v_mad_i64_i32 v[64:65], s[56:57], v64, s40, v[24:25]
	v_mad_i64_i32 v[66:67], s[56:57], v66, s40, v[24:25]
	v_mad_i64_i32 v[68:69], s[56:57], v68, s40, v[24:25]
	v_mad_i64_i32 v[70:71], s[56:57], v70, s40, v[24:25]
	v_mad_i64_i32 v[72:73], s[56:57], v72, s40, v[24:25]
	v_mad_i64_i32 v[74:75], s[56:57], v74, s40, v[24:25]
	v_mad_i64_i32 v[76:77], s[56:57], v76, s40, v[24:25]
	v_mad_i64_i32 v[78:79], s[56:57], v78, s40, v[24:25]
	global_load_dword v37, v[48:49], off nt
	global_load_dword v40, v[50:51], off nt
	global_load_dword v47, v[52:53], off nt
	global_load_dword v80, v[54:55], off nt
	global_load_dword v81, v[56:57], off nt
	global_load_dword v82, v[58:59], off nt
	global_load_dword v83, v[60:61], off nt
	global_load_dword v84, v[62:63], off nt
	global_load_dword v85, v[64:65], off nt
	global_load_dword v86, v[66:67], off nt
	global_load_dword v87, v[68:69], off nt
	global_load_dword v88, v[70:71], off nt
	global_load_dword v89, v[72:73], off nt
	global_load_dword v90, v[74:75], off nt
	global_load_dword v91, v[76:77], off nt
	global_load_dword v92, v[78:79], off nt
	s_add_i32 s9, s9, 16
	s_add_i32 s8, s8, 16
	s_add_i32 s16, s16, -16
	v_add_u32_e32 v48, s17, v0
	v_add_u32_e32 v50, s58, v1
	v_add_u32_e32 v52, s17, v8
	v_add_u32_e32 v54, s58, v5
	v_add_u32_e32 v56, s17, v10
	v_add_u32_e32 v58, s58, v7
	v_add_u32_e32 v60, s17, v12
	v_add_u32_e32 v62, s58, v9
	v_add_u32_e32 v64, s17, v14
	v_add_u32_e32 v66, s58, v11
	v_add_u32_e32 v68, s17, v16
	v_add_u32_e32 v70, s58, v13
	v_add_u32_e32 v72, s17, v18
	v_add_u32_e32 v74, s58, v15
	v_add_u32_e32 v76, s17, v20
	v_add_u32_e32 v78, s58, v17
	s_cmp_lg_u32 s16, 0
	v_mad_u64_u32 v[48:49], s[56:57], v48, s35, v[4:5]
	v_mad_u64_u32 v[50:51], s[56:57], v50, s35, v[4:5]
	v_mad_u64_u32 v[52:53], s[56:57], v52, s35, v[4:5]
	v_mad_u64_u32 v[54:55], s[56:57], v54, s35, v[4:5]
	v_mad_u64_u32 v[56:57], s[56:57], v56, s35, v[4:5]
	v_mad_u64_u32 v[58:59], s[56:57], v58, s35, v[4:5]
	v_mad_u64_u32 v[60:61], s[56:57], v60, s35, v[4:5]
	v_mad_u64_u32 v[62:63], s[56:57], v62, s35, v[4:5]
	v_mad_u64_u32 v[64:65], s[56:57], v64, s35, v[4:5]
	v_mad_u64_u32 v[66:67], s[56:57], v66, s35, v[4:5]
	v_mad_u64_u32 v[68:69], s[56:57], v68, s35, v[4:5]
	v_mad_u64_u32 v[70:71], s[56:57], v70, s35, v[4:5]
	v_mad_u64_u32 v[72:73], s[56:57], v72, s35, v[4:5]
	v_mad_u64_u32 v[74:75], s[56:57], v74, s35, v[4:5]
	v_mad_u64_u32 v[76:77], s[56:57], v76, s35, v[4:5]
	v_mad_u64_u32 v[78:79], s[56:57], v78, s35, v[4:5]
	s_waitcnt vmcnt(15)
	ds_write_b32 v48, v37
	s_waitcnt vmcnt(14)
	ds_write_b32 v50, v40
	s_waitcnt vmcnt(13)
	ds_write_b32 v52, v47
	s_waitcnt vmcnt(12)
	ds_write_b32 v54, v80
	s_waitcnt vmcnt(11)
	ds_write_b32 v56, v81
	s_waitcnt vmcnt(10)
	ds_write_b32 v58, v82
	s_waitcnt vmcnt(9)
	ds_write_b32 v60, v83
	s_waitcnt vmcnt(8)
	ds_write_b32 v62, v84
	s_waitcnt vmcnt(7)
	ds_write_b32 v64, v85
	s_waitcnt vmcnt(6)
	ds_write_b32 v66, v86
	s_waitcnt vmcnt(5)
	ds_write_b32 v68, v87
	s_waitcnt vmcnt(4)
	ds_write_b32 v70, v88
	s_waitcnt vmcnt(3)
	ds_write_b32 v72, v89
	s_waitcnt vmcnt(2)
	ds_write_b32 v74, v90
	s_waitcnt vmcnt(1)
	ds_write_b32 v76, v91
	s_waitcnt vmcnt(0)
	ds_write_b32 v78, v92
	s_cbranch_scc1 .LBB0_26
	s_waitcnt lgkmcnt(0)
	ds_read2_b32 v[34:35], v42 offset1:33
	ds_read2_b32 v[30:31], v42 offset0:66 offset1:99
	ds_read2_b32 v[28:29], v42 offset0:132 offset1:165
	ds_read2_b32 v[26:27], v42 offset0:198 offset1:231
	v_add_u32_e32 v2, s2, v41
	v_mul_hi_i32 v19, v2, s41
	v_lshrrev_b32_e32 v21, 31, v19
	v_ashrrev_i32_e32 v19, 5, v19
	v_add_u32_e32 v19, v19, v21
	v_mul_lo_u32 v21, v19, s42
	v_sub_u32_e32 v2, v2, v21
	v_cmp_lt_i32_e32 vcc, s43, v2
	s_and_saveexec_b64 s[8:9], vcc
	s_xor_b64 s[8:9], exec, s[8:9]
	v_and_b32_e32 v21, 0x7fffffe0, v2
	v_lshl_add_u32 v19, v19, 6, v21
	v_and_or_b32 v19, v2, 3, v19
	v_lshlrev_b32_e32 v21, 1, v2
	v_lshrrev_b32_e32 v2, 2, v2
	v_and_b32_e32 v21, 24, v21
	v_and_b32_e32 v2, 4, v2
	v_or3_b32 v2, v19, v21, v2
	v_add_u32_e32 v32, 0x180, v2
	s_andn2_saveexec_b64 s[8:9], s[8:9]
	v_lshl_add_u32 v32, v19, 7, v2
	s_or_b64 exec, exec, s[8:9]
	s_mul_i32 s9, s6, 0xc0000
	s_mul_hi_i32 s8, s6, 0xc0000
	s_add_u32 s9, s21, s9
	s_addc_u32 s16, s22, s8
	s_lshl_b32 s7, s7, 1
	s_add_u32 s8, s9, s7
	s_addc_u32 s9, s16, 0
	v_lshlrev_b32_e32 v2, 1, v6
	v_lshl_add_u64 v[24:25], s[8:9], 0, v[2:3]
	s_waitcnt lgkmcnt(3)
	v_bfe_u32 v2, v34, 16, 1
	v_add3_u32 v2, v34, v2, s37
	v_bfe_u32 v19, v35, 16, 1
	v_lshrrev_b32_e32 v2, 16, v2
	v_add3_u32 v19, v35, v19, s37
	v_and_or_b32 v34, v19, s38, v2
	s_waitcnt lgkmcnt(2)
	v_bfe_u32 v2, v30, 16, 1
	v_add3_u32 v2, v30, v2, s37
	v_bfe_u32 v19, v31, 16, 1
	v_lshrrev_b32_e32 v2, 16, v2
	v_add3_u32 v19, v31, v19, s37
	v_and_or_b32 v35, v19, s38, v2
	s_waitcnt lgkmcnt(1)
	v_bfe_u32 v2, v28, 16, 1
	v_add3_u32 v2, v28, v2, s37
	v_bfe_u32 v19, v29, 16, 1
	v_lshrrev_b32_e32 v2, 16, v2
	v_add3_u32 v19, v29, v19, s37
	v_and_or_b32 v36, v19, s38, v2
	s_waitcnt lgkmcnt(0)
	v_bfe_u32 v2, v26, 16, 1
	v_add3_u32 v2, v26, v2, s37
	v_bfe_u32 v19, v27, 16, 1
	v_ashrrev_i32_e32 v33, 31, v32
	v_lshrrev_b32_e32 v2, 16, v2
	v_add3_u32 v19, v27, v19, s37
	v_lshlrev_b64 v[26:27], 10, v[32:33]
	v_and_or_b32 v37, v19, s38, v2
	v_lshl_add_u64 v[26:27], v[24:25], 0, v[26:27]
	global_store_dwordx4 v[26:27], v[34:37], off nt
	ds_read2_b32 v[34:35], v42 offset0:8 offset1:41
	ds_read2_b32 v[30:31], v42 offset0:74 offset1:107
	ds_read2_b32 v[28:29], v42 offset0:140 offset1:173
	ds_read2_b32 v[26:27], v42 offset0:206 offset1:239
	v_add_u32_e32 v2, s2, v43
	v_mul_hi_i32 v19, v2, s41
	v_lshrrev_b32_e32 v21, 31, v19
	v_ashrrev_i32_e32 v19, 5, v19
	v_add_u32_e32 v19, v19, v21
	v_mul_lo_u32 v21, v19, s42
	v_sub_u32_e32 v2, v2, v21
	v_cmp_lt_i32_e32 vcc, s43, v2
	s_and_saveexec_b64 s[8:9], vcc
	s_xor_b64 s[8:9], exec, s[8:9]
	v_and_b32_e32 v21, 0x7fffffe0, v2
	v_lshl_add_u32 v19, v19, 6, v21
	v_and_or_b32 v19, v2, 3, v19
	v_lshlrev_b32_e32 v21, 1, v2
	v_lshrrev_b32_e32 v2, 2, v2
	v_and_b32_e32 v21, 24, v21
	v_and_b32_e32 v2, 4, v2
	v_or3_b32 v2, v19, v21, v2
	v_add_u32_e32 v32, 0x180, v2
	s_andn2_saveexec_b64 s[8:9], s[8:9]
	v_lshl_add_u32 v32, v19, 7, v2
	s_or_b64 exec, exec, s[8:9]
	s_waitcnt lgkmcnt(3)
	v_bfe_u32 v2, v34, 16, 1
	v_add3_u32 v2, v34, v2, s37
	v_bfe_u32 v19, v35, 16, 1
	v_lshrrev_b32_e32 v2, 16, v2
	v_add3_u32 v19, v35, v19, s37
	v_and_or_b32 v34, v19, s38, v2
	s_waitcnt lgkmcnt(2)
	v_bfe_u32 v2, v30, 16, 1
	v_add3_u32 v2, v30, v2, s37
	v_bfe_u32 v19, v31, 16, 1
	v_lshrrev_b32_e32 v2, 16, v2
	v_add3_u32 v19, v31, v19, s37
	v_and_or_b32 v35, v19, s38, v2
	s_waitcnt lgkmcnt(1)
	v_bfe_u32 v2, v28, 16, 1
	v_add3_u32 v2, v28, v2, s37
	v_bfe_u32 v19, v29, 16, 1
	v_lshrrev_b32_e32 v2, 16, v2
	v_add3_u32 v19, v29, v19, s37
	v_and_or_b32 v36, v19, s38, v2
	s_waitcnt lgkmcnt(0)
	v_bfe_u32 v2, v26, 16, 1
	v_add3_u32 v2, v26, v2, s37
	v_bfe_u32 v19, v27, 16, 1
	v_ashrrev_i32_e32 v33, 31, v32
	v_lshrrev_b32_e32 v2, 16, v2
	v_add3_u32 v19, v27, v19, s37
	v_lshlrev_b64 v[26:27], 10, v[32:33]
	v_and_or_b32 v37, v19, s38, v2
	v_lshl_add_u64 v[26:27], v[24:25], 0, v[26:27]
	global_store_dwordx4 v[26:27], v[34:37], off nt
	ds_read2_b32 v[34:35], v42 offset0:16 offset1:49
	ds_read2_b32 v[30:31], v42 offset0:82 offset1:115
	ds_read2_b32 v[28:29], v42 offset0:148 offset1:181
	ds_read2_b32 v[26:27], v42 offset0:214 offset1:247
	v_add_u32_e32 v2, s2, v44
	v_mul_hi_i32 v19, v2, s41
	v_lshrrev_b32_e32 v21, 31, v19
	v_ashrrev_i32_e32 v19, 5, v19
	v_add_u32_e32 v19, v19, v21
	v_mul_lo_u32 v21, v19, s42
	v_sub_u32_e32 v2, v2, v21
	v_cmp_lt_i32_e32 vcc, s43, v2
	s_and_saveexec_b64 s[8:9], vcc
	s_xor_b64 s[8:9], exec, s[8:9]
	v_and_b32_e32 v21, 0x7fffffe0, v2
	v_lshl_add_u32 v19, v19, 6, v21
	v_and_or_b32 v19, v2, 3, v19
	v_lshlrev_b32_e32 v21, 1, v2
	v_lshrrev_b32_e32 v2, 2, v2
	v_and_b32_e32 v21, 24, v21
	v_and_b32_e32 v2, 4, v2
	v_or3_b32 v2, v19, v21, v2
	v_add_u32_e32 v32, 0x180, v2
	s_andn2_saveexec_b64 s[8:9], s[8:9]
	v_lshl_add_u32 v32, v19, 7, v2
	s_or_b64 exec, exec, s[8:9]
	s_waitcnt lgkmcnt(3)
	v_bfe_u32 v2, v34, 16, 1
	v_add3_u32 v2, v34, v2, s37
	v_bfe_u32 v19, v35, 16, 1
	v_lshrrev_b32_e32 v2, 16, v2
	v_add3_u32 v19, v35, v19, s37
	v_and_or_b32 v34, v19, s38, v2
	s_waitcnt lgkmcnt(2)
	v_bfe_u32 v2, v30, 16, 1
	v_add3_u32 v2, v30, v2, s37
	v_bfe_u32 v19, v31, 16, 1
	v_lshrrev_b32_e32 v2, 16, v2
	v_add3_u32 v19, v31, v19, s37
	v_and_or_b32 v35, v19, s38, v2
	s_waitcnt lgkmcnt(1)
	v_bfe_u32 v2, v28, 16, 1
	v_add3_u32 v2, v28, v2, s37
	v_bfe_u32 v19, v29, 16, 1
	v_lshrrev_b32_e32 v2, 16, v2
	v_add3_u32 v19, v29, v19, s37
	v_and_or_b32 v36, v19, s38, v2
	s_waitcnt lgkmcnt(0)
	v_bfe_u32 v2, v26, 16, 1
	v_add3_u32 v2, v26, v2, s37
	v_bfe_u32 v19, v27, 16, 1
	v_ashrrev_i32_e32 v33, 31, v32
	v_lshrrev_b32_e32 v2, 16, v2
	v_add3_u32 v19, v27, v19, s37
	v_lshlrev_b64 v[26:27], 10, v[32:33]
	v_and_or_b32 v37, v19, s38, v2
	v_lshl_add_u64 v[26:27], v[24:25], 0, v[26:27]
	global_store_dwordx4 v[26:27], v[34:37], off nt
	ds_read2_b32 v[34:35], v42 offset0:24 offset1:57
	ds_read2_b32 v[32:33], v42 offset0:90 offset1:123
	ds_read2_b32 v[28:29], v42 offset0:156 offset1:189
	ds_read2_b32 v[26:27], v42 offset0:222 offset1:255
	v_add_u32_e32 v2, s2, v45
	v_mul_hi_i32 v19, v2, s41
	v_lshrrev_b32_e32 v21, 31, v19
	v_ashrrev_i32_e32 v19, 5, v19
	v_add_u32_e32 v19, v19, v21
	v_mul_lo_u32 v21, v19, s42
	v_sub_u32_e32 v2, v2, v21
	v_cmp_lt_i32_e32 vcc, s43, v2
	s_and_saveexec_b64 s[8:9], vcc
	s_xor_b64 s[8:9], exec, s[8:9]
	v_and_b32_e32 v21, 0x7fffffe0, v2
	v_lshl_add_u32 v19, v19, 6, v21
	v_and_or_b32 v19, v2, 3, v19
	v_lshlrev_b32_e32 v21, 1, v2
	v_lshrrev_b32_e32 v2, 2, v2
	v_and_b32_e32 v21, 24, v21
	v_and_b32_e32 v2, 4, v2
	v_or3_b32 v2, v19, v21, v2
	v_add_u32_e32 v30, 0x180, v2
	s_andn2_saveexec_b64 s[8:9], s[8:9]
	v_lshl_add_u32 v30, v19, 7, v2
	s_or_b64 exec, exec, s[8:9]
	s_waitcnt lgkmcnt(3)
	v_bfe_u32 v19, v34, 16, 1
	v_bfe_u32 v2, v35, 16, 1
	v_add3_u32 v19, v34, v19, s37
	v_add3_u32 v2, v35, v2, s37
	v_lshrrev_b32_e32 v19, 16, v19
	v_and_or_b32 v34, v2, s38, v19
	s_waitcnt lgkmcnt(2)
	v_bfe_u32 v19, v32, 16, 1
	v_bfe_u32 v2, v33, 16, 1
	v_add3_u32 v19, v32, v19, s37
	v_add3_u32 v2, v33, v2, s37
	v_lshrrev_b32_e32 v19, 16, v19
	v_and_or_b32 v35, v2, s38, v19
	s_waitcnt lgkmcnt(1)
	v_bfe_u32 v19, v28, 16, 1
	v_bfe_u32 v2, v29, 16, 1
	v_add3_u32 v19, v28, v19, s37
	v_add3_u32 v2, v29, v2, s37
	v_lshrrev_b32_e32 v19, 16, v19
	v_and_or_b32 v36, v2, s38, v19
	s_waitcnt lgkmcnt(0)
	v_bfe_u32 v19, v26, 16, 1
	v_bfe_u32 v2, v27, 16, 1
	v_add3_u32 v19, v26, v19, s37
	v_ashrrev_i32_e32 v31, 31, v30
	v_add3_u32 v2, v27, v2, s37
	v_lshrrev_b32_e32 v19, 16, v19
	v_lshlrev_b64 v[26:27], 10, v[30:31]
	v_and_or_b32 v37, v2, s38, v19
	v_lshl_add_u64 v[24:25], v[24:25], 0, v[26:27]
	global_store_dwordx4 v[24:25], v[34:37], off nt
	s_waitcnt lgkmcnt(0)

.LBB0_47:
	s_lshl_b32 s17, s9, 1
	s_lshl_b32 s56, s8, 1
	v_add_u32_e32 v48, s17, v2
	v_add_u32_e32 v50, s56, v19
	v_add_u32_e32 v52, s17, v26
	v_add_u32_e32 v54, s56, v21
	v_add_u32_e32 v56, s17, v28
	v_add_u32_e32 v58, s56, v23
	v_add_u32_e32 v60, s17, v30
	v_add_u32_e32 v62, s56, v27
	v_add_u32_e32 v64, s17, v32
	v_add_u32_e32 v66, s56, v29
	v_add_u32_e32 v68, s17, v34
	v_add_u32_e32 v70, s56, v31
	v_add_u32_e32 v72, s17, v36
	v_add_u32_e32 v74, s56, v33
	v_add_u32_e32 v76, s17, v38
	v_add_u32_e32 v78, s56, v35
	v_ashrrev_i32_e32 v49, 31, v48
	v_ashrrev_i32_e32 v51, 31, v50
	v_ashrrev_i32_e32 v53, 31, v52
	v_ashrrev_i32_e32 v55, 31, v54
	v_ashrrev_i32_e32 v57, 31, v56
	v_ashrrev_i32_e32 v59, 31, v58
	v_ashrrev_i32_e32 v61, 31, v60
	v_ashrrev_i32_e32 v63, 31, v62
	v_ashrrev_i32_e32 v65, 31, v64
	v_ashrrev_i32_e32 v67, 31, v66
	v_ashrrev_i32_e32 v69, 31, v68
	v_ashrrev_i32_e32 v71, 31, v70
	v_ashrrev_i32_e32 v73, 31, v72
	v_ashrrev_i32_e32 v75, 31, v74
	v_ashrrev_i32_e32 v77, 31, v76
	v_ashrrev_i32_e32 v79, 31, v78
	v_lshlrev_b64 v[48:49], 13, v[48:49]
	v_lshlrev_b64 v[50:51], 13, v[50:51]
	v_lshlrev_b64 v[52:53], 13, v[52:53]
	v_lshlrev_b64 v[54:55], 13, v[54:55]
	v_lshlrev_b64 v[56:57], 13, v[56:57]
	v_lshlrev_b64 v[58:59], 13, v[58:59]
	v_lshlrev_b64 v[60:61], 13, v[60:61]
	v_lshlrev_b64 v[62:63], 13, v[62:63]
	v_lshlrev_b64 v[64:65], 13, v[64:65]
	v_lshlrev_b64 v[66:67], 13, v[66:67]
	v_lshlrev_b64 v[68:69], 13, v[68:69]
	v_lshlrev_b64 v[70:71], 13, v[70:71]
	v_lshlrev_b64 v[72:73], 13, v[72:73]
	v_lshlrev_b64 v[74:75], 13, v[74:75]
	v_lshlrev_b64 v[76:77], 13, v[76:77]
	v_lshlrev_b64 v[78:79], 13, v[78:79]
	v_lshl_add_u64 v[48:49], v[24:25], 0, v[48:49]
	v_lshl_add_u64 v[50:51], v[24:25], 0, v[50:51]
	v_lshl_add_u64 v[52:53], v[24:25], 0, v[52:53]
	v_lshl_add_u64 v[54:55], v[24:25], 0, v[54:55]
	v_lshl_add_u64 v[56:57], v[24:25], 0, v[56:57]
	v_lshl_add_u64 v[58:59], v[24:25], 0, v[58:59]
	v_lshl_add_u64 v[60:61], v[24:25], 0, v[60:61]
	v_lshl_add_u64 v[62:63], v[24:25], 0, v[62:63]
	v_lshl_add_u64 v[64:65], v[24:25], 0, v[64:65]
	v_lshl_add_u64 v[66:67], v[24:25], 0, v[66:67]
	v_lshl_add_u64 v[68:69], v[24:25], 0, v[68:69]
	v_lshl_add_u64 v[70:71], v[24:25], 0, v[70:71]
	v_lshl_add_u64 v[72:73], v[24:25], 0, v[72:73]
	v_lshl_add_u64 v[74:75], v[24:25], 0, v[74:75]
	v_lshl_add_u64 v[76:77], v[24:25], 0, v[76:77]
	v_lshl_add_u64 v[78:79], v[24:25], 0, v[78:79]
	global_load_dword v37, v[48:49], off nt
	global_load_dword v40, v[50:51], off nt
	global_load_dword v47, v[52:53], off nt
	global_load_dword v80, v[54:55], off nt
	global_load_dword v81, v[56:57], off nt
	global_load_dword v82, v[58:59], off nt
	global_load_dword v83, v[60:61], off nt
	global_load_dword v84, v[62:63], off nt
	global_load_dword v85, v[64:65], off nt
	global_load_dword v86, v[66:67], off nt
	global_load_dword v87, v[68:69], off nt
	global_load_dword v88, v[70:71], off nt
	global_load_dword v89, v[72:73], off nt
	global_load_dword v90, v[74:75], off nt
	global_load_dword v91, v[76:77], off nt
	global_load_dword v92, v[78:79], off nt
	s_add_i32 s9, s9, 16
	s_add_i32 s8, s8, 16
	s_add_i32 s16, s16, -16
	v_add_u32_e32 v48, s17, v0
	v_add_u32_e32 v50, s56, v1
	v_add_u32_e32 v52, s17, v8
	v_add_u32_e32 v54, s56, v5
	v_add_u32_e32 v56, s17, v10
	v_add_u32_e32 v58, s56, v7
	v_add_u32_e32 v60, s17, v12
	v_add_u32_e32 v62, s56, v9
	v_add_u32_e32 v64, s17, v14
	v_add_u32_e32 v66, s56, v11
	v_add_u32_e32 v68, s17, v16
	v_add_u32_e32 v70, s56, v13
	v_add_u32_e32 v72, s17, v18
	v_add_u32_e32 v74, s56, v15
	v_add_u32_e32 v76, s17, v20
	v_add_u32_e32 v78, s56, v17
	s_cmp_lg_u32 s16, 0
	v_mad_u64_u32 v[48:49], s[56:57], v48, s35, v[4:5]
	v_mad_u64_u32 v[50:51], s[56:57], v50, s35, v[4:5]
	v_mad_u64_u32 v[52:53], s[56:57], v52, s35, v[4:5]
	v_mad_u64_u32 v[54:55], s[56:57], v54, s35, v[4:5]
	v_mad_u64_u32 v[56:57], s[56:57], v56, s35, v[4:5]
	v_mad_u64_u32 v[58:59], s[56:57], v58, s35, v[4:5]
	v_mad_u64_u32 v[60:61], s[56:57], v60, s35, v[4:5]
	v_mad_u64_u32 v[62:63], s[56:57], v62, s35, v[4:5]
	v_mad_u64_u32 v[64:65], s[56:57], v64, s35, v[4:5]
	v_mad_u64_u32 v[66:67], s[56:57], v66, s35, v[4:5]
	v_mad_u64_u32 v[68:69], s[56:57], v68, s35, v[4:5]
	v_mad_u64_u32 v[70:71], s[56:57], v70, s35, v[4:5]
	v_mad_u64_u32 v[72:73], s[56:57], v72, s35, v[4:5]
	v_mad_u64_u32 v[74:75], s[56:57], v74, s35, v[4:5]
	v_mad_u64_u32 v[76:77], s[56:57], v76, s35, v[4:5]
	v_mad_u64_u32 v[78:79], s[56:57], v78, s35, v[4:5]
	s_waitcnt vmcnt(15)
	ds_write_b32 v48, v37
	s_waitcnt vmcnt(14)
	ds_write_b32 v50, v40
	s_waitcnt vmcnt(13)
	ds_write_b32 v52, v47
	s_waitcnt vmcnt(12)
	ds_write_b32 v54, v80
	s_waitcnt vmcnt(11)
	ds_write_b32 v56, v81
	s_waitcnt vmcnt(10)
	ds_write_b32 v58, v82
	s_waitcnt vmcnt(9)
	ds_write_b32 v60, v83
	s_waitcnt vmcnt(8)
	ds_write_b32 v62, v84
	s_waitcnt vmcnt(7)
	ds_write_b32 v64, v85
	s_waitcnt vmcnt(6)
	ds_write_b32 v66, v86
	s_waitcnt vmcnt(5)
	ds_write_b32 v68, v87
	s_waitcnt vmcnt(4)
	ds_write_b32 v70, v88
	s_waitcnt vmcnt(3)
	ds_write_b32 v72, v89
	s_waitcnt vmcnt(2)
	ds_write_b32 v74, v90
	s_waitcnt vmcnt(1)
	ds_write_b32 v76, v91
	s_waitcnt vmcnt(0)
	ds_write_b32 v78, v92
	s_cbranch_scc1 .LBB0_47
	s_waitcnt lgkmcnt(0)
	s_mul_i32 s9, s6, 0x1600000
	ds_read2_b32 v[28:29], v42 offset1:8
	s_mul_hi_i32 s8, s6, 0x1600000
	s_add_u32 s9, s23, s9
	ds_read2_b32 v[32:33], v42 offset0:33 offset1:41
	s_addc_u32 s16, s24, s8
	s_lshl_b32 s7, s7, 1
	s_add_u32 s8, s9, s7
	ds_read2_b32 v[34:35], v42 offset0:66 offset1:74
	s_addc_u32 s9, s16, 0
	v_lshlrev_b32_e32 v2, 1, v6
	ds_read2_b32 v[36:37], v42 offset0:99 offset1:107
	v_lshl_add_u64 v[30:31], s[8:9], 0, v[2:3]
	s_waitcnt lgkmcnt(3)
	v_bfe_u32 v2, v28, 16, 1
	v_add3_u32 v2, v28, v2, s37
	s_waitcnt lgkmcnt(2)
	v_bfe_u32 v19, v32, 16, 1
	ds_read2_b32 v[48:49], v42 offset0:132 offset1:140
	v_lshrrev_b32_e32 v2, 16, v2
	v_add3_u32 v19, v32, v19, s37
	ds_read2_b32 v[50:51], v42 offset0:165 offset1:173
	v_and_or_b32 v24, v19, s38, v2
	s_waitcnt lgkmcnt(3)
	v_bfe_u32 v2, v34, 16, 1
	v_add3_u32 v2, v34, v2, s37
	s_waitcnt lgkmcnt(2)
	v_bfe_u32 v19, v36, 16, 1
	ds_read2_b32 v[52:53], v42 offset0:198 offset1:206
	v_lshrrev_b32_e32 v2, 16, v2
	v_add3_u32 v19, v36, v19, s37
	ds_read2_b32 v[54:55], v42 offset0:231 offset1:239
	v_and_or_b32 v25, v19, s38, v2
	s_waitcnt lgkmcnt(3)
	v_bfe_u32 v2, v48, 16, 1
	v_add3_u32 v2, v48, v2, s37
	s_waitcnt lgkmcnt(2)
	v_bfe_u32 v19, v50, 16, 1
	v_lshrrev_b32_e32 v2, 16, v2
	v_add3_u32 v19, v50, v19, s37
	v_and_or_b32 v26, v19, s38, v2
	s_waitcnt lgkmcnt(1)
	v_bfe_u32 v2, v52, 16, 1
	v_add3_u32 v2, v52, v2, s37
	s_waitcnt lgkmcnt(0)
	v_bfe_u32 v19, v54, 16, 1
	v_lshrrev_b32_e32 v2, 16, v2
	v_add3_u32 v19, v54, v19, s37
	v_and_or_b32 v27, v19, s38, v2
	v_add_u32_e32 v2, s2, v41
	v_mad_i64_i32 v[56:57], s[8:9], v2, s45, v[30:31]
	v_bfe_u32 v2, v29, 16, 1
	v_add3_u32 v2, v29, v2, s37
	v_bfe_u32 v19, v33, 16, 1
	v_lshrrev_b32_e32 v2, 16, v2
	v_add3_u32 v19, v33, v19, s37
	global_store_dwordx4 v[56:57], v[24:27], off nt
	ds_read2_b32 v[28:29], v42 offset0:16 offset1:24
	s_waitcnt lgkmcnt(0)
	v_bfe_u32 v21, v29, 16, 1
	v_and_or_b32 v24, v19, s38, v2
	v_bfe_u32 v2, v35, 16, 1
	v_add3_u32 v2, v35, v2, s37
	v_bfe_u32 v19, v37, 16, 1
	v_lshrrev_b32_e32 v2, 16, v2
	v_add3_u32 v19, v37, v19, s37
	v_and_or_b32 v25, v19, s38, v2
	v_bfe_u32 v2, v49, 16, 1
	v_add3_u32 v2, v49, v2, s37
	v_bfe_u32 v19, v51, 16, 1
	v_lshrrev_b32_e32 v2, 16, v2
	v_add3_u32 v19, v51, v19, s37
	v_and_or_b32 v26, v19, s38, v2
	v_bfe_u32 v2, v53, 16, 1
	v_add3_u32 v2, v53, v2, s37
	v_bfe_u32 v19, v55, 16, 1
	v_lshrrev_b32_e32 v2, 16, v2
	v_add3_u32 v19, v55, v19, s37
	v_and_or_b32 v27, v19, s38, v2
	v_add_u32_e32 v2, s2, v43
	v_mad_i64_i32 v[32:33], s[8:9], v2, s45, v[30:31]
	global_store_dwordx4 v[32:33], v[24:27], off nt
	ds_read2_b32 v[32:33], v42 offset0:49 offset1:57
	ds_read2_b32 v[34:35], v42 offset0:82 offset1:90
	ds_read2_b32 v[36:37], v42 offset0:115 offset1:123
	v_bfe_u32 v2, v28, 16, 1
	v_add3_u32 v2, v28, v2, s37
	s_waitcnt lgkmcnt(2)
	v_bfe_u32 v19, v32, 16, 1
	ds_read2_b32 v[48:49], v42 offset0:148 offset1:156
	v_lshrrev_b32_e32 v2, 16, v2
	v_add3_u32 v19, v32, v19, s37
	ds_read2_b32 v[50:51], v42 offset0:181 offset1:189
	v_and_or_b32 v24, v19, s38, v2
	s_waitcnt lgkmcnt(3)
	v_bfe_u32 v2, v34, 16, 1
	v_add3_u32 v2, v34, v2, s37
	s_waitcnt lgkmcnt(2)
	v_bfe_u32 v19, v36, 16, 1
	ds_read2_b32 v[52:53], v42 offset0:214 offset1:222
	v_lshrrev_b32_e32 v2, 16, v2
	v_add3_u32 v19, v36, v19, s37
	ds_read2_b32 v[54:55], v42 offset0:247 offset1:255
	v_and_or_b32 v25, v19, s38, v2
	s_waitcnt lgkmcnt(3)
	v_bfe_u32 v2, v48, 16, 1
	v_add3_u32 v2, v48, v2, s37
	s_waitcnt lgkmcnt(2)
	v_bfe_u32 v19, v50, 16, 1
	v_lshrrev_b32_e32 v2, 16, v2
	v_add3_u32 v19, v50, v19, s37
	v_and_or_b32 v26, v19, s38, v2
	s_waitcnt lgkmcnt(1)
	v_bfe_u32 v2, v52, 16, 1
	v_add3_u32 v2, v52, v2, s37
	s_waitcnt lgkmcnt(0)
	v_bfe_u32 v19, v54, 16, 1
	v_lshrrev_b32_e32 v2, 16, v2
	v_add3_u32 v19, v54, v19, s37
	v_and_or_b32 v27, v19, s38, v2
	v_add_u32_e32 v2, s2, v44
	v_bfe_u32 v19, v33, 16, 1
	v_add3_u32 v21, v29, v21, s37
	v_mad_i64_i32 v[56:57], s[8:9], v2, s45, v[30:31]
	v_add3_u32 v19, v33, v19, s37
	v_lshrrev_b32_e32 v21, 16, v21
	global_store_dwordx4 v[56:57], v[24:27], off nt
	v_add_u32_e32 v2, s2, v45
	v_mad_i64_i32 v[28:29], s[8:9], v2, s45, v[30:31]
	v_and_or_b32 v24, v19, s38, v21
	v_bfe_u32 v21, v35, 16, 1
	v_bfe_u32 v19, v37, 16, 1
	v_add3_u32 v21, v35, v21, s37
	v_add3_u32 v19, v37, v19, s37
	v_lshrrev_b32_e32 v21, 16, v21
	v_and_or_b32 v25, v19, s38, v21
	v_bfe_u32 v21, v49, 16, 1
	v_bfe_u32 v19, v51, 16, 1
	v_add3_u32 v21, v49, v21, s37
	v_add3_u32 v19, v51, v19, s37
	v_lshrrev_b32_e32 v21, 16, v21
	v_and_or_b32 v26, v19, s38, v21
	v_bfe_u32 v21, v53, 16, 1
	v_bfe_u32 v19, v55, 16, 1
	v_add3_u32 v21, v53, v21, s37
	v_add3_u32 v19, v55, v19, s37
	v_lshrrev_b32_e32 v21, 16, v21
	v_and_or_b32 v27, v19, s38, v21
	global_store_dwordx4 v[28:29], v[24:27], off nt
	s_waitcnt lgkmcnt(0)

.LBB0_52:
	s_lshl_b32 s17, s9, 1
	s_lshl_b32 s58, s8, 1
	v_add_u32_e32 v37, s17, v2
	v_add_u32_e32 v40, s58, v19
	v_add_u32_e32 v47, s17, v26
	v_add_u32_e32 v54, s58, v21
	v_add_u32_e32 v56, s17, v28
	v_add_u32_e32 v58, s58, v23
	v_add_u32_e32 v60, s17, v30
	v_add_u32_e32 v62, s58, v27
	v_add_u32_e32 v64, s17, v32
	v_add_u32_e32 v66, s58, v29
	v_add_u32_e32 v68, s17, v34
	v_add_u32_e32 v70, s58, v31
	v_add_u32_e32 v72, s17, v36
	v_add_u32_e32 v74, s58, v33
	v_add_u32_e32 v76, s17, v38
	v_add_u32_e32 v78, s58, v35
	v_mad_i64_i32 v[48:49], s[56:57], v37, s47, v[24:25]
	v_mad_i64_i32 v[50:51], s[56:57], v40, s47, v[24:25]
	v_mad_i64_i32 v[52:53], s[56:57], v47, s47, v[24:25]
	v_mad_i64_i32 v[54:55], s[56:57], v54, s47, v[24:25]
	v_mad_i64_i32 v[56:57], s[56:57], v56, s47, v[24:25]
	v_mad_i64_i32 v[58:59], s[56:57], v58, s47, v[24:25]
	v_mad_i64_i32 v[60:61], s[56:57], v60, s47, v[24:25]
	v_mad_i64_i32 v[62:63], s[56:57], v62, s47, v[24:25]
	v_mad_i64_i32 v[64:65], s[56:57], v64, s47, v[24:25]
	v_mad_i64_i32 v[66:67], s[56:57], v66, s47, v[24:25]
	v_mad_i64_i32 v[68:69], s[56:57], v68, s47, v[24:25]
	v_mad_i64_i32 v[70:71], s[56:57], v70, s47, v[24:25]
	v_mad_i64_i32 v[72:73], s[56:57], v72, s47, v[24:25]
	v_mad_i64_i32 v[74:75], s[56:57], v74, s47, v[24:25]
	v_mad_i64_i32 v[76:77], s[56:57], v76, s47, v[24:25]
	v_mad_i64_i32 v[78:79], s[56:57], v78, s47, v[24:25]
	global_load_dword v37, v[48:49], off nt
	global_load_dword v40, v[50:51], off nt
	global_load_dword v47, v[52:53], off nt
	global_load_dword v80, v[54:55], off nt
	global_load_dword v81, v[56:57], off nt
	global_load_dword v82, v[58:59], off nt
	global_load_dword v83, v[60:61], off nt
	global_load_dword v84, v[62:63], off nt
	global_load_dword v85, v[64:65], off nt
	global_load_dword v86, v[66:67], off nt
	global_load_dword v87, v[68:69], off nt
	global_load_dword v88, v[70:71], off nt
	global_load_dword v89, v[72:73], off nt
	global_load_dword v90, v[74:75], off nt
	global_load_dword v91, v[76:77], off nt
	global_load_dword v92, v[78:79], off nt
	s_add_i32 s9, s9, 16
	s_add_i32 s8, s8, 16
	s_add_i32 s16, s16, -16
	v_add_u32_e32 v48, s17, v0
	v_add_u32_e32 v50, s58, v1
	v_add_u32_e32 v52, s17, v8
	v_add_u32_e32 v54, s58, v5
	v_add_u32_e32 v56, s17, v10
	v_add_u32_e32 v58, s58, v7
	v_add_u32_e32 v60, s17, v12
	v_add_u32_e32 v62, s58, v9
	v_add_u32_e32 v64, s17, v14
	v_add_u32_e32 v66, s58, v11
	v_add_u32_e32 v68, s17, v16
	v_add_u32_e32 v70, s58, v13
	v_add_u32_e32 v72, s17, v18
	v_add_u32_e32 v74, s58, v15
	v_add_u32_e32 v76, s17, v20
	v_add_u32_e32 v78, s58, v17
	s_cmp_lg_u32 s16, 0
	v_mad_u64_u32 v[48:49], s[56:57], v48, s35, v[4:5]
	v_mad_u64_u32 v[50:51], s[56:57], v50, s35, v[4:5]
	v_mad_u64_u32 v[52:53], s[56:57], v52, s35, v[4:5]
	v_mad_u64_u32 v[54:55], s[56:57], v54, s35, v[4:5]
	v_mad_u64_u32 v[56:57], s[56:57], v56, s35, v[4:5]
	v_mad_u64_u32 v[58:59], s[56:57], v58, s35, v[4:5]
	v_mad_u64_u32 v[60:61], s[56:57], v60, s35, v[4:5]
	v_mad_u64_u32 v[62:63], s[56:57], v62, s35, v[4:5]
	v_mad_u64_u32 v[64:65], s[56:57], v64, s35, v[4:5]
	v_mad_u64_u32 v[66:67], s[56:57], v66, s35, v[4:5]
	v_mad_u64_u32 v[68:69], s[56:57], v68, s35, v[4:5]
	v_mad_u64_u32 v[70:71], s[56:57], v70, s35, v[4:5]
	v_mad_u64_u32 v[72:73], s[56:57], v72, s35, v[4:5]
	v_mad_u64_u32 v[74:75], s[56:57], v74, s35, v[4:5]
	v_mad_u64_u32 v[76:77], s[56:57], v76, s35, v[4:5]
	v_mad_u64_u32 v[78:79], s[56:57], v78, s35, v[4:5]
	s_waitcnt vmcnt(15)
	ds_write_b32 v48, v37
	s_waitcnt vmcnt(14)
	ds_write_b32 v50, v40
	s_waitcnt vmcnt(13)
	ds_write_b32 v52, v47
	s_waitcnt vmcnt(12)
	ds_write_b32 v54, v80
	s_waitcnt vmcnt(11)
	ds_write_b32 v56, v81
	s_waitcnt vmcnt(10)
	ds_write_b32 v58, v82
	s_waitcnt vmcnt(9)
	ds_write_b32 v60, v83
	s_waitcnt vmcnt(8)
	ds_write_b32 v62, v84
	s_waitcnt vmcnt(7)
	ds_write_b32 v64, v85
	s_waitcnt vmcnt(6)
	ds_write_b32 v66, v86
	s_waitcnt vmcnt(5)
	ds_write_b32 v68, v87
	s_waitcnt vmcnt(4)
	ds_write_b32 v70, v88
	s_waitcnt vmcnt(3)
	ds_write_b32 v72, v89
	s_waitcnt vmcnt(2)
	ds_write_b32 v74, v90
	s_waitcnt vmcnt(1)
	ds_write_b32 v76, v91
	s_waitcnt vmcnt(0)
	ds_write_b32 v78, v92
	s_cbranch_scc1 .LBB0_52
	s_waitcnt lgkmcnt(0)
	s_mul_i32 s9, s6, 0x2c00000
	s_mul_hi_i32 s8, s6, 0x2c00000
	s_add_u32 s9, s25, s9
	ds_read2_b32 v[28:29], v42 offset1:8
	s_addc_u32 s16, s26, s8
	s_and_b32 s2, 0xffff, s2
	ds_read2_b32 v[32:33], v42 offset0:33 offset1:41
	s_and_b32 s7, 0xffff, s7
	s_lshl_b32 s2, s2, 1
	s_add_u32 s8, s9, s2
	ds_read2_b32 v[34:35], v42 offset0:66 offset1:74
	s_addc_u32 s9, s16, 0
	v_lshlrev_b32_e32 v2, 1, v6
	ds_read2_b32 v[36:37], v42 offset0:99 offset1:107
	v_lshl_add_u64 v[30:31], s[8:9], 0, v[2:3]
	s_waitcnt lgkmcnt(3)
	v_bfe_u32 v2, v28, 16, 1
	v_add3_u32 v2, v28, v2, s37
	s_waitcnt lgkmcnt(2)
	v_bfe_u32 v19, v32, 16, 1
	ds_read2_b32 v[48:49], v42 offset0:132 offset1:140
	v_lshrrev_b32_e32 v2, 16, v2
	v_add3_u32 v19, v32, v19, s37
	ds_read2_b32 v[50:51], v42 offset0:165 offset1:173
	v_and_or_b32 v24, v19, s38, v2
	s_waitcnt lgkmcnt(3)
	v_bfe_u32 v2, v34, 16, 1
	v_add3_u32 v2, v34, v2, s37
	s_waitcnt lgkmcnt(2)
	v_bfe_u32 v19, v36, 16, 1
	ds_read2_b32 v[52:53], v42 offset0:198 offset1:206
	v_lshrrev_b32_e32 v2, 16, v2
	v_add3_u32 v19, v36, v19, s37
	ds_read2_b32 v[54:55], v42 offset0:231 offset1:239
	v_and_or_b32 v25, v19, s38, v2
	s_waitcnt lgkmcnt(3)
	v_bfe_u32 v2, v48, 16, 1
	v_add3_u32 v2, v48, v2, s37
	s_waitcnt lgkmcnt(2)
	v_bfe_u32 v19, v50, 16, 1
	v_lshrrev_b32_e32 v2, 16, v2
	v_add3_u32 v19, v50, v19, s37
	v_and_or_b32 v26, v19, s38, v2
	s_waitcnt lgkmcnt(1)
	v_bfe_u32 v2, v52, 16, 1
	v_add3_u32 v2, v52, v2, s37
	s_waitcnt lgkmcnt(0)
	v_bfe_u32 v19, v54, 16, 1
	v_lshrrev_b32_e32 v2, 16, v2
	v_add3_u32 v19, v54, v19, s37
	v_and_or_b32 v27, v19, s38, v2
	v_add_u32_e32 v2, s7, v41
	v_mul_hi_i32 v19, v2, s48
	v_lshrrev_b32_e32 v21, 31, v19
	v_ashrrev_i32_e32 v19, 10, v19
	v_add_u32_e32 v19, v19, v21
	v_mul_i32_i24_e32 v21, 0x1600, v19
	v_sub_u32_e32 v21, v2, v21
	v_ashrrev_i16_e32 v23, 15, v21
	v_lshrrev_b16_e32 v23, 9, v23
	v_add_u16_e32 v21, v21, v23
	v_ashrrev_i32_e32 v23, 31, v2
	v_lshrrev_b32_e32 v23, 25, v23
	v_add_u32_e32 v23, v2, v23
	v_ashrrev_i16_e32 v21, 7, v21
	v_and_b32_e32 v23, 0xffffff80, v23
	v_lshlrev_b32_sdwa v21, v46, sext(v21) dst_sel:DWORD dst_unused:UNUSED_PAD src0_sel:DWORD src1_sel:WORD_0
	v_lshlrev_b32_e32 v19, 7, v19
	v_sub_u32_e32 v2, v2, v23
	v_add3_u32 v56, v19, v2, v21
	v_ashrrev_i32_e32 v57, 31, v56
	v_bfe_u32 v2, v29, 16, 1
	v_lshlrev_b64 v[56:57], 12, v[56:57]
	v_add3_u32 v2, v29, v2, s37
	v_bfe_u32 v19, v33, 16, 1
	v_lshl_add_u64 v[56:57], v[30:31], 0, v[56:57]
	v_lshrrev_b32_e32 v2, 16, v2
	v_add3_u32 v19, v33, v19, s37
	global_store_dwordx4 v[56:57], v[24:27], off nt
	ds_read2_b32 v[32:33], v42 offset0:16 offset1:24
	s_nop 0
	v_and_or_b32 v24, v19, s38, v2
	v_bfe_u32 v2, v35, 16, 1
	v_add3_u32 v2, v35, v2, s37
	v_bfe_u32 v19, v37, 16, 1
	v_lshrrev_b32_e32 v2, 16, v2
	v_add3_u32 v19, v37, v19, s37
	v_and_or_b32 v25, v19, s38, v2
	v_bfe_u32 v2, v49, 16, 1
	v_add3_u32 v2, v49, v2, s37
	v_bfe_u32 v19, v51, 16, 1
	v_lshrrev_b32_e32 v2, 16, v2
	v_add3_u32 v19, v51, v19, s37
	v_and_or_b32 v26, v19, s38, v2
	v_bfe_u32 v2, v53, 16, 1
	v_add3_u32 v2, v53, v2, s37
	v_bfe_u32 v19, v55, 16, 1
	v_lshrrev_b32_e32 v2, 16, v2
	v_add3_u32 v19, v55, v19, s37
	v_and_or_b32 v27, v19, s38, v2
	v_add_u32_e32 v2, s7, v43
	v_mul_hi_i32 v19, v2, s48
	v_lshrrev_b32_e32 v21, 31, v19
	v_ashrrev_i32_e32 v19, 10, v19
	v_add_u32_e32 v19, v19, v21
	v_mul_i32_i24_e32 v21, 0x1600, v19
	v_sub_u32_e32 v21, v2, v21
	v_ashrrev_i16_e32 v23, 15, v21
	v_lshrrev_b16_e32 v23, 9, v23
	v_add_u16_e32 v21, v21, v23
	v_ashrrev_i32_e32 v23, 31, v2
	v_lshrrev_b32_e32 v23, 25, v23
	v_add_u32_e32 v23, v2, v23
	v_ashrrev_i16_e32 v21, 7, v21
	v_and_b32_e32 v23, 0xffffff80, v23
	v_lshlrev_b32_sdwa v21, v46, sext(v21) dst_sel:DWORD dst_unused:UNUSED_PAD src0_sel:DWORD src1_sel:WORD_0
	v_lshlrev_b32_e32 v19, 7, v19
	v_sub_u32_e32 v2, v2, v23
	v_add3_u32 v28, v19, v2, v21
	v_ashrrev_i32_e32 v29, 31, v28
	v_lshlrev_b64 v[28:29], 12, v[28:29]
	v_lshl_add_u64 v[28:29], v[30:31], 0, v[28:29]
	global_store_dwordx4 v[28:29], v[24:27], off nt
	ds_read2_b32 v[28:29], v42 offset0:49 offset1:57
	ds_read2_b32 v[34:35], v42 offset0:82 offset1:90
	ds_read2_b32 v[36:37], v42 offset0:115 offset1:123
	s_waitcnt lgkmcnt(3)
	v_bfe_u32 v2, v32, 16, 1
	v_add3_u32 v2, v32, v2, s37
	s_waitcnt lgkmcnt(2)
	v_bfe_u32 v19, v28, 16, 1
	ds_read2_b32 v[48:49], v42 offset0:148 offset1:156
	v_lshrrev_b32_e32 v2, 16, v2
	v_add3_u32 v19, v28, v19, s37
	ds_read2_b32 v[50:51], v42 offset0:181 offset1:189
	v_and_or_b32 v24, v19, s38, v2
	s_waitcnt lgkmcnt(3)
	v_bfe_u32 v2, v34, 16, 1
	v_add3_u32 v2, v34, v2, s37
	s_waitcnt lgkmcnt(2)
	v_bfe_u32 v19, v36, 16, 1
	ds_read2_b32 v[52:53], v42 offset0:214 offset1:222
	v_lshrrev_b32_e32 v2, 16, v2
	v_add3_u32 v19, v36, v19, s37
	ds_read2_b32 v[54:55], v42 offset0:247 offset1:255
	v_and_or_b32 v25, v19, s38, v2
	s_waitcnt lgkmcnt(3)
	v_bfe_u32 v2, v48, 16, 1
	v_add3_u32 v2, v48, v2, s37
	s_waitcnt lgkmcnt(2)
	v_bfe_u32 v19, v50, 16, 1
	v_lshrrev_b32_e32 v2, 16, v2
	v_add3_u32 v19, v50, v19, s37
	v_and_or_b32 v26, v19, s38, v2
	s_waitcnt lgkmcnt(1)
	v_bfe_u32 v2, v52, 16, 1
	v_add3_u32 v2, v52, v2, s37
	s_waitcnt lgkmcnt(0)
	v_bfe_u32 v19, v54, 16, 1
	v_lshrrev_b32_e32 v2, 16, v2
	v_add3_u32 v19, v54, v19, s37
	v_and_or_b32 v27, v19, s38, v2
	v_add_u32_e32 v2, s7, v44
	v_mul_hi_i32 v19, v2, s48
	v_lshrrev_b32_e32 v21, 31, v19
	v_ashrrev_i32_e32 v19, 10, v19
	v_add_u32_e32 v19, v19, v21
	v_mul_i32_i24_e32 v21, 0x1600, v19
	v_sub_u32_e32 v21, v2, v21
	v_ashrrev_i16_e32 v23, 15, v21
	v_lshrrev_b16_e32 v23, 9, v23
	v_add_u16_e32 v21, v21, v23
	v_ashrrev_i32_e32 v23, 31, v2
	v_lshrrev_b32_e32 v23, 25, v23
	v_add_u32_e32 v23, v2, v23
	v_ashrrev_i16_e32 v21, 7, v21
	v_and_b32_e32 v23, 0xffffff80, v23
	v_lshlrev_b32_sdwa v21, v46, sext(v21) dst_sel:DWORD dst_unused:UNUSED_PAD src0_sel:DWORD src1_sel:WORD_0
	v_lshlrev_b32_e32 v19, 7, v19
	v_sub_u32_e32 v2, v2, v23
	v_add3_u32 v56, v19, v2, v21
	v_add_u32_e32 v2, s7, v45
	v_mul_hi_i32 v19, v2, s48
	v_lshrrev_b32_e32 v21, 31, v19
	v_ashrrev_i32_e32 v19, 10, v19
	v_add_u32_e32 v19, v19, v21
	v_mul_i32_i24_e32 v21, 0x1600, v19
	v_sub_u32_e32 v21, v2, v21
	v_ashrrev_i16_e32 v23, 15, v21
	v_lshrrev_b16_e32 v23, 9, v23
	v_add_u16_e32 v21, v21, v23
	v_ashrrev_i32_e32 v23, 31, v2
	v_lshrrev_b32_e32 v23, 25, v23
	v_add_u32_e32 v23, v2, v23
	v_ashrrev_i16_e32 v21, 7, v21
	v_and_b32_e32 v23, 0xffffff80, v23
	v_lshlrev_b32_sdwa v21, v46, sext(v21) dst_sel:DWORD dst_unused:UNUSED_PAD src0_sel:DWORD src1_sel:WORD_0
	v_lshlrev_b32_e32 v19, 7, v19
	v_sub_u32_e32 v2, v2, v23
	v_ashrrev_i32_e32 v57, 31, v56
	v_add3_u32 v28, v19, v2, v21
	v_bfe_u32 v19, v33, 16, 1
	v_lshlrev_b64 v[56:57], 12, v[56:57]
	v_bfe_u32 v2, v29, 16, 1
	v_add3_u32 v19, v33, v19, s37
	v_lshl_add_u64 v[56:57], v[30:31], 0, v[56:57]
	v_add3_u32 v2, v29, v2, s37
	v_lshrrev_b32_e32 v19, 16, v19
	global_store_dwordx4 v[56:57], v[24:27], off nt
	v_ashrrev_i32_e32 v29, 31, v28
	v_lshlrev_b64 v[28:29], 12, v[28:29]
	v_and_or_b32 v24, v2, s38, v19
	v_bfe_u32 v19, v35, 16, 1
	v_bfe_u32 v2, v37, 16, 1
	v_add3_u32 v19, v35, v19, s37
	v_add3_u32 v2, v37, v2, s37
	v_lshrrev_b32_e32 v19, 16, v19
	v_and_or_b32 v25, v2, s38, v19
	v_bfe_u32 v19, v49, 16, 1
	v_bfe_u32 v2, v51, 16, 1
	v_add3_u32 v19, v49, v19, s37
	v_add3_u32 v2, v51, v2, s37
	v_lshrrev_b32_e32 v19, 16, v19
	v_and_or_b32 v26, v2, s38, v19
	v_bfe_u32 v19, v53, 16, 1
	v_bfe_u32 v2, v55, 16, 1
	v_add3_u32 v19, v53, v19, s37
	v_add3_u32 v2, v55, v2, s37
	v_lshrrev_b32_e32 v19, 16, v19
	v_and_or_b32 v27, v2, s38, v19
	v_lshl_add_u64 v[28:29], v[30:31], 0, v[28:29]
	global_store_dwordx4 v[28:29], v[24:27], off nt
	s_waitcnt lgkmcnt(0)

.LBB0_58:
	s_lshl_b32 s58, s56, 1
	s_lshl_b32 s59, s17, 1
	v_add_u32_e32 v48, s58, v2
	v_add_u32_e32 v50, s59, v19
	v_add_u32_e32 v52, s58, v28
	v_add_u32_e32 v54, s59, v21
	v_add_u32_e32 v56, s58, v30
	v_add_u32_e32 v58, s59, v23
	v_add_u32_e32 v60, s58, v32
	v_add_u32_e32 v62, s59, v29
	v_add_u32_e32 v64, s58, v34
	v_add_u32_e32 v66, s59, v31
	v_add_u32_e32 v68, s58, v36
	v_add_u32_e32 v70, s59, v33
	v_add_u32_e32 v72, s58, v38
	v_add_u32_e32 v74, s59, v35
	v_add_u32_e32 v76, s58, v40
	v_add_u32_e32 v78, s59, v37
	v_ashrrev_i32_e32 v49, 31, v48
	v_ashrrev_i32_e32 v51, 31, v50
	v_ashrrev_i32_e32 v53, 31, v52
	v_ashrrev_i32_e32 v55, 31, v54
	v_ashrrev_i32_e32 v57, 31, v56
	v_ashrrev_i32_e32 v59, 31, v58
	v_ashrrev_i32_e32 v61, 31, v60
	v_ashrrev_i32_e32 v63, 31, v62
	v_ashrrev_i32_e32 v65, 31, v64
	v_ashrrev_i32_e32 v67, 31, v66
	v_ashrrev_i32_e32 v69, 31, v68
	v_ashrrev_i32_e32 v71, 31, v70
	v_ashrrev_i32_e32 v73, 31, v72
	v_ashrrev_i32_e32 v75, 31, v74
	v_ashrrev_i32_e32 v77, 31, v76
	v_ashrrev_i32_e32 v79, 31, v78
	v_lshlrev_b64 v[48:49], 13, v[48:49]
	v_lshlrev_b64 v[50:51], 13, v[50:51]
	v_lshlrev_b64 v[52:53], 13, v[52:53]
	v_lshlrev_b64 v[54:55], 13, v[54:55]
	v_lshlrev_b64 v[56:57], 13, v[56:57]
	v_lshlrev_b64 v[58:59], 13, v[58:59]
	v_lshlrev_b64 v[60:61], 13, v[60:61]
	v_lshlrev_b64 v[62:63], 13, v[62:63]
	v_lshlrev_b64 v[64:65], 13, v[64:65]
	v_lshlrev_b64 v[66:67], 13, v[66:67]
	v_lshlrev_b64 v[68:69], 13, v[68:69]
	v_lshlrev_b64 v[70:71], 13, v[70:71]
	v_lshlrev_b64 v[72:73], 13, v[72:73]
	v_lshlrev_b64 v[74:75], 13, v[74:75]
	v_lshlrev_b64 v[76:77], 13, v[76:77]
	v_lshlrev_b64 v[78:79], 13, v[78:79]
	v_lshl_add_u64 v[48:49], v[26:27], 0, v[48:49]
	v_lshl_add_u64 v[50:51], v[26:27], 0, v[50:51]
	v_lshl_add_u64 v[52:53], v[26:27], 0, v[52:53]
	v_lshl_add_u64 v[54:55], v[26:27], 0, v[54:55]
	v_lshl_add_u64 v[56:57], v[26:27], 0, v[56:57]
	v_lshl_add_u64 v[58:59], v[26:27], 0, v[58:59]
	v_lshl_add_u64 v[60:61], v[26:27], 0, v[60:61]
	v_lshl_add_u64 v[62:63], v[26:27], 0, v[62:63]
	v_lshl_add_u64 v[64:65], v[26:27], 0, v[64:65]
	v_lshl_add_u64 v[66:67], v[26:27], 0, v[66:67]
	v_lshl_add_u64 v[68:69], v[26:27], 0, v[68:69]
	v_lshl_add_u64 v[70:71], v[26:27], 0, v[70:71]
	v_lshl_add_u64 v[72:73], v[26:27], 0, v[72:73]
	v_lshl_add_u64 v[74:75], v[26:27], 0, v[74:75]
	v_lshl_add_u64 v[76:77], v[26:27], 0, v[76:77]
	v_lshl_add_u64 v[78:79], v[26:27], 0, v[78:79]
	global_load_dword v47, v[48:49], off nt
	global_load_dword v80, v[50:51], off nt
	global_load_dword v81, v[52:53], off nt
	global_load_dword v82, v[54:55], off nt
	global_load_dword v83, v[56:57], off nt
	global_load_dword v84, v[58:59], off nt
	global_load_dword v85, v[60:61], off nt
	global_load_dword v86, v[62:63], off nt
	global_load_dword v87, v[64:65], off nt
	global_load_dword v88, v[66:67], off nt
	global_load_dword v89, v[68:69], off nt
	global_load_dword v90, v[70:71], off nt
	global_load_dword v91, v[72:73], off nt
	global_load_dword v92, v[74:75], off nt
	global_load_dword v93, v[76:77], off nt
	global_load_dword v94, v[78:79], off nt
	s_add_i32 s56, s56, 16
	s_add_i32 s17, s17, 16
	s_add_i32 s57, s57, -16
	v_add_u32_e32 v48, s58, v0
	v_add_u32_e32 v50, s59, v1
	v_add_u32_e32 v52, s58, v8
	v_add_u32_e32 v54, s59, v5
	v_add_u32_e32 v56, s58, v10
	v_add_u32_e32 v58, s59, v7
	v_add_u32_e32 v60, s58, v12
	v_add_u32_e32 v62, s59, v9
	v_add_u32_e32 v64, s58, v14
	v_add_u32_e32 v66, s59, v11
	v_add_u32_e32 v68, s58, v16
	v_add_u32_e32 v70, s59, v13
	v_add_u32_e32 v72, s58, v18
	v_add_u32_e32 v74, s59, v15
	v_add_u32_e32 v76, s58, v20
	v_add_u32_e32 v78, s59, v17
	s_cmp_lg_u32 s57, 0
	v_mad_u64_u32 v[48:49], s[58:59], v48, s35, v[4:5]
	v_mad_u64_u32 v[50:51], s[58:59], v50, s35, v[4:5]
	v_mad_u64_u32 v[52:53], s[58:59], v52, s35, v[4:5]
	v_mad_u64_u32 v[54:55], s[58:59], v54, s35, v[4:5]
	v_mad_u64_u32 v[56:57], s[58:59], v56, s35, v[4:5]
	v_mad_u64_u32 v[58:59], s[58:59], v58, s35, v[4:5]
	v_mad_u64_u32 v[60:61], s[58:59], v60, s35, v[4:5]
	v_mad_u64_u32 v[62:63], s[58:59], v62, s35, v[4:5]
	v_mad_u64_u32 v[64:65], s[58:59], v64, s35, v[4:5]
	v_mad_u64_u32 v[66:67], s[58:59], v66, s35, v[4:5]
	v_mad_u64_u32 v[68:69], s[58:59], v68, s35, v[4:5]
	v_mad_u64_u32 v[70:71], s[58:59], v70, s35, v[4:5]
	v_mad_u64_u32 v[72:73], s[58:59], v72, s35, v[4:5]
	v_mad_u64_u32 v[74:75], s[58:59], v74, s35, v[4:5]
	v_mad_u64_u32 v[76:77], s[58:59], v76, s35, v[4:5]
	v_mad_u64_u32 v[78:79], s[58:59], v78, s35, v[4:5]
	s_waitcnt vmcnt(15)
	ds_write_b32 v48, v47
	s_waitcnt vmcnt(14)
	ds_write_b32 v50, v80
	s_waitcnt vmcnt(13)
	ds_write_b32 v52, v81
	s_waitcnt vmcnt(12)
	ds_write_b32 v54, v82
	s_waitcnt vmcnt(11)
	ds_write_b32 v56, v83
	s_waitcnt vmcnt(10)
	ds_write_b32 v58, v84
	s_waitcnt vmcnt(9)
	ds_write_b32 v60, v85
	s_waitcnt vmcnt(8)
	ds_write_b32 v62, v86
	s_waitcnt vmcnt(7)
	ds_write_b32 v64, v87
	s_waitcnt vmcnt(6)
	ds_write_b32 v66, v88
	s_waitcnt vmcnt(5)
	ds_write_b32 v68, v89
	s_waitcnt vmcnt(4)
	ds_write_b32 v70, v90
	s_waitcnt vmcnt(3)
	ds_write_b32 v72, v91
	s_waitcnt vmcnt(2)
	ds_write_b32 v74, v92
	s_waitcnt vmcnt(1)
	ds_write_b32 v76, v93
	s_waitcnt vmcnt(0)
	ds_write_b32 v78, v94
	s_cbranch_scc1 .LBB0_58
	s_waitcnt lgkmcnt(0)
	s_lshl_b64 s[8:9], s[8:9], 1
	ds_read2_b32 v[30:31], v42 offset1:8
	s_add_u32 s8, s27, s8
	ds_read2_b32 v[34:35], v42 offset0:33 offset1:41
	s_addc_u32 s9, s28, s9
	s_lshl_b32 s16, s16, 1
	s_add_u32 s8, s8, s16
	ds_read2_b32 v[36:37], v42 offset0:66 offset1:74
	s_addc_u32 s9, s9, 0
	v_lshlrev_b32_e32 v2, 1, v6
	ds_read2_b32 v[48:49], v42 offset0:99 offset1:107
	v_lshl_add_u64 v[32:33], s[8:9], 0, v[2:3]
	s_waitcnt lgkmcnt(3)
	v_bfe_u32 v2, v30, 16, 1
	v_add3_u32 v2, v30, v2, s37
	s_waitcnt lgkmcnt(2)
	v_bfe_u32 v19, v34, 16, 1
	ds_read2_b32 v[50:51], v42 offset0:132 offset1:140
	v_lshrrev_b32_e32 v2, 16, v2
	v_add3_u32 v19, v34, v19, s37
	ds_read2_b32 v[52:53], v42 offset0:165 offset1:173
	v_and_or_b32 v26, v19, s38, v2
	s_waitcnt lgkmcnt(3)
	v_bfe_u32 v2, v36, 16, 1
	v_add3_u32 v2, v36, v2, s37
	s_waitcnt lgkmcnt(2)
	v_bfe_u32 v19, v48, 16, 1
	ds_read2_b32 v[54:55], v42 offset0:198 offset1:206
	v_lshrrev_b32_e32 v2, 16, v2
	v_add3_u32 v19, v48, v19, s37
	ds_read2_b32 v[56:57], v42 offset0:231 offset1:239
	v_and_or_b32 v27, v19, s38, v2
	s_waitcnt lgkmcnt(3)
	v_bfe_u32 v2, v50, 16, 1
	v_add3_u32 v2, v50, v2, s37
	s_waitcnt lgkmcnt(2)
	v_bfe_u32 v19, v52, 16, 1
	v_lshrrev_b32_e32 v2, 16, v2
	v_add3_u32 v19, v52, v19, s37
	v_and_or_b32 v28, v19, s38, v2
	s_waitcnt lgkmcnt(1)
	v_bfe_u32 v2, v54, 16, 1
	v_add3_u32 v2, v54, v2, s37
	s_waitcnt lgkmcnt(0)
	v_bfe_u32 v19, v56, 16, 1
	v_lshrrev_b32_e32 v2, 16, v2
	v_add3_u32 v19, v56, v19, s37
	v_add_u32_e32 v58, s2, v41
	v_and_or_b32 v29, v19, s38, v2
	v_ashrrev_i32_e32 v59, 31, v58
	v_bfe_u32 v2, v31, 16, 1
	v_lshlrev_b64 v[58:59], 12, v[58:59]
	v_add3_u32 v2, v31, v2, s37
	v_bfe_u32 v19, v35, 16, 1
	v_lshl_add_u64 v[58:59], v[32:33], 0, v[58:59]
	v_lshrrev_b32_e32 v2, 16, v2
	v_add3_u32 v19, v35, v19, s37
	global_store_dwordx4 v[58:59], v[26:29], off nt
	v_add_u32_e32 v30, s2, v43
	v_ashrrev_i32_e32 v31, 31, v30
	v_and_or_b32 v26, v19, s38, v2
	v_bfe_u32 v2, v37, 16, 1
	v_add3_u32 v2, v37, v2, s37
	v_bfe_u32 v19, v49, 16, 1
	v_lshrrev_b32_e32 v2, 16, v2
	v_add3_u32 v19, v49, v19, s37
	v_and_or_b32 v27, v19, s38, v2
	v_bfe_u32 v2, v51, 16, 1
	v_add3_u32 v2, v51, v2, s37
	v_bfe_u32 v19, v53, 16, 1
	v_lshrrev_b32_e32 v2, 16, v2
	v_add3_u32 v19, v53, v19, s37
	v_and_or_b32 v28, v19, s38, v2
	v_bfe_u32 v2, v55, 16, 1
	v_add3_u32 v2, v55, v2, s37
	v_bfe_u32 v19, v57, 16, 1
	v_lshrrev_b32_e32 v2, 16, v2
	v_add3_u32 v19, v57, v19, s37
	v_lshlrev_b64 v[30:31], 12, v[30:31]
	v_and_or_b32 v29, v19, s38, v2
	ds_read2_b32 v[34:35], v42 offset0:16 offset1:24
	v_lshl_add_u64 v[30:31], v[32:33], 0, v[30:31]
	global_store_dwordx4 v[30:31], v[26:29], off nt
	ds_read2_b32 v[30:31], v42 offset0:49 offset1:57
	ds_read2_b32 v[36:37], v42 offset0:82 offset1:90
	ds_read2_b32 v[48:49], v42 offset0:115 offset1:123
	s_waitcnt lgkmcnt(3)
	v_bfe_u32 v2, v34, 16, 1
	v_add3_u32 v2, v34, v2, s37
	s_waitcnt lgkmcnt(2)
	v_bfe_u32 v19, v30, 16, 1
	ds_read2_b32 v[50:51], v42 offset0:148 offset1:156
	v_lshrrev_b32_e32 v2, 16, v2
	v_add3_u32 v19, v30, v19, s37
	ds_read2_b32 v[52:53], v42 offset0:181 offset1:189
	v_and_or_b32 v26, v19, s38, v2
	s_waitcnt lgkmcnt(3)
	v_bfe_u32 v2, v36, 16, 1
	v_add3_u32 v2, v36, v2, s37
	s_waitcnt lgkmcnt(2)
	v_bfe_u32 v19, v48, 16, 1
	ds_read2_b32 v[54:55], v42 offset0:214 offset1:222
	v_lshrrev_b32_e32 v2, 16, v2
	v_add3_u32 v19, v48, v19, s37
	ds_read2_b32 v[56:57], v42 offset0:247 offset1:255
	v_and_or_b32 v27, v19, s38, v2
	s_waitcnt lgkmcnt(3)
	v_bfe_u32 v2, v50, 16, 1
	v_add3_u32 v2, v50, v2, s37
	s_waitcnt lgkmcnt(2)
	v_bfe_u32 v19, v52, 16, 1
	v_lshrrev_b32_e32 v2, 16, v2
	v_add3_u32 v19, v52, v19, s37
	v_and_or_b32 v28, v19, s38, v2
	s_waitcnt lgkmcnt(1)
	v_bfe_u32 v2, v54, 16, 1
	v_add3_u32 v2, v54, v2, s37
	s_waitcnt lgkmcnt(0)
	v_bfe_u32 v19, v56, 16, 1
	v_lshrrev_b32_e32 v2, 16, v2
	v_add3_u32 v19, v56, v19, s37
	v_add_u32_e32 v58, s2, v44
	v_and_or_b32 v29, v19, s38, v2
	v_ashrrev_i32_e32 v59, 31, v58
	v_bfe_u32 v19, v35, 16, 1
	v_lshlrev_b64 v[58:59], 12, v[58:59]
	v_bfe_u32 v2, v31, 16, 1
	v_add3_u32 v19, v35, v19, s37
	v_lshl_add_u64 v[58:59], v[32:33], 0, v[58:59]
	v_add3_u32 v2, v31, v2, s37
	v_lshrrev_b32_e32 v19, 16, v19
	global_store_dwordx4 v[58:59], v[26:29], off nt
	v_add_u32_e32 v30, s2, v45
	v_ashrrev_i32_e32 v31, 31, v30
	v_and_or_b32 v26, v2, s38, v19
	v_bfe_u32 v19, v37, 16, 1
	v_bfe_u32 v2, v49, 16, 1
	v_add3_u32 v19, v37, v19, s37
	v_add3_u32 v2, v49, v2, s37
	v_lshrrev_b32_e32 v19, 16, v19
	v_and_or_b32 v27, v2, s38, v19
	v_bfe_u32 v19, v51, 16, 1
	v_bfe_u32 v2, v53, 16, 1
	v_add3_u32 v19, v51, v19, s37
	v_add3_u32 v2, v53, v2, s37
	v_lshrrev_b32_e32 v19, 16, v19
	v_and_or_b32 v28, v2, s38, v19
	v_bfe_u32 v19, v55, 16, 1
	v_bfe_u32 v2, v57, 16, 1
	v_add3_u32 v19, v55, v19, s37
	v_add3_u32 v2, v57, v2, s37
	v_lshrrev_b32_e32 v19, 16, v19
	v_lshlrev_b64 v[30:31], 12, v[30:31]
	v_and_or_b32 v29, v2, s38, v19
	v_lshl_add_u64 v[30:31], v[32:33], 0, v[30:31]
	global_store_dwordx4 v[30:31], v[26:29], off nt
	s_waitcnt lgkmcnt(0)
	s_mov_b64 s[8:9], 0

.LBB0_62:
	s_lshl_b32 s56, s9, 1
	s_lshl_b32 s57, s2, 1
	v_add_u32_e32 v48, s56, v2
	v_add_u32_e32 v50, s57, v19
	v_add_u32_e32 v52, s56, v26
	v_add_u32_e32 v54, s57, v21
	v_add_u32_e32 v56, s56, v28
	v_add_u32_e32 v58, s57, v23
	v_add_u32_e32 v60, s56, v30
	v_add_u32_e32 v62, s57, v27
	v_add_u32_e32 v64, s56, v32
	v_add_u32_e32 v66, s57, v29
	v_add_u32_e32 v68, s56, v34
	v_add_u32_e32 v70, s57, v31
	v_add_u32_e32 v72, s56, v36
	v_add_u32_e32 v74, s57, v33
	v_add_u32_e32 v76, s56, v38
	v_add_u32_e32 v78, s57, v35
	v_ashrrev_i32_e32 v49, 31, v48
	v_ashrrev_i32_e32 v51, 31, v50
	v_ashrrev_i32_e32 v53, 31, v52
	v_ashrrev_i32_e32 v55, 31, v54
	v_ashrrev_i32_e32 v57, 31, v56
	v_ashrrev_i32_e32 v59, 31, v58
	v_ashrrev_i32_e32 v61, 31, v60
	v_ashrrev_i32_e32 v63, 31, v62
	v_ashrrev_i32_e32 v65, 31, v64
	v_ashrrev_i32_e32 v67, 31, v66
	v_ashrrev_i32_e32 v69, 31, v68
	v_ashrrev_i32_e32 v71, 31, v70
	v_ashrrev_i32_e32 v73, 31, v72
	v_ashrrev_i32_e32 v75, 31, v74
	v_ashrrev_i32_e32 v77, 31, v76
	v_ashrrev_i32_e32 v79, 31, v78
	v_lshlrev_b64 v[48:49], 13, v[48:49]
	v_lshlrev_b64 v[50:51], 13, v[50:51]
	v_lshlrev_b64 v[52:53], 13, v[52:53]
	v_lshlrev_b64 v[54:55], 13, v[54:55]
	v_lshlrev_b64 v[56:57], 13, v[56:57]
	v_lshlrev_b64 v[58:59], 13, v[58:59]
	v_lshlrev_b64 v[60:61], 13, v[60:61]
	v_lshlrev_b64 v[62:63], 13, v[62:63]
	v_lshlrev_b64 v[64:65], 13, v[64:65]
	v_lshlrev_b64 v[66:67], 13, v[66:67]
	v_lshlrev_b64 v[68:69], 13, v[68:69]
	v_lshlrev_b64 v[70:71], 13, v[70:71]
	v_lshlrev_b64 v[72:73], 13, v[72:73]
	v_lshlrev_b64 v[74:75], 13, v[74:75]
	v_lshlrev_b64 v[76:77], 13, v[76:77]
	v_lshlrev_b64 v[78:79], 13, v[78:79]
	v_lshl_add_u64 v[48:49], v[24:25], 0, v[48:49]
	v_lshl_add_u64 v[50:51], v[24:25], 0, v[50:51]
	v_lshl_add_u64 v[52:53], v[24:25], 0, v[52:53]
	v_lshl_add_u64 v[54:55], v[24:25], 0, v[54:55]
	v_lshl_add_u64 v[56:57], v[24:25], 0, v[56:57]
	v_lshl_add_u64 v[58:59], v[24:25], 0, v[58:59]
	v_lshl_add_u64 v[60:61], v[24:25], 0, v[60:61]
	v_lshl_add_u64 v[62:63], v[24:25], 0, v[62:63]
	v_lshl_add_u64 v[64:65], v[24:25], 0, v[64:65]
	v_lshl_add_u64 v[66:67], v[24:25], 0, v[66:67]
	v_lshl_add_u64 v[68:69], v[24:25], 0, v[68:69]
	v_lshl_add_u64 v[70:71], v[24:25], 0, v[70:71]
	v_lshl_add_u64 v[72:73], v[24:25], 0, v[72:73]
	v_lshl_add_u64 v[74:75], v[24:25], 0, v[74:75]
	v_lshl_add_u64 v[76:77], v[24:25], 0, v[76:77]
	v_lshl_add_u64 v[78:79], v[24:25], 0, v[78:79]
	global_load_dword v37, v[48:49], off nt
	global_load_dword v40, v[50:51], off nt
	global_load_dword v47, v[52:53], off nt
	global_load_dword v80, v[54:55], off nt
	global_load_dword v81, v[56:57], off nt
	global_load_dword v82, v[58:59], off nt
	global_load_dword v83, v[60:61], off nt
	global_load_dword v84, v[62:63], off nt
	global_load_dword v85, v[64:65], off nt
	global_load_dword v86, v[66:67], off nt
	global_load_dword v87, v[68:69], off nt
	global_load_dword v88, v[70:71], off nt
	global_load_dword v89, v[72:73], off nt
	global_load_dword v90, v[74:75], off nt
	global_load_dword v91, v[76:77], off nt
	global_load_dword v92, v[78:79], off nt
	s_add_i32 s9, s9, 16
	s_add_i32 s2, s2, 16
	s_add_i32 s17, s17, -16
	v_add_u32_e32 v48, s56, v0
	v_add_u32_e32 v50, s57, v1
	v_add_u32_e32 v52, s56, v8
	v_add_u32_e32 v54, s57, v5
	v_add_u32_e32 v56, s56, v10
	v_add_u32_e32 v58, s57, v7
	v_add_u32_e32 v60, s56, v12
	v_add_u32_e32 v62, s57, v9
	v_add_u32_e32 v64, s56, v14
	v_add_u32_e32 v66, s57, v11
	v_add_u32_e32 v68, s56, v16
	v_add_u32_e32 v70, s57, v13
	v_add_u32_e32 v72, s56, v18
	v_add_u32_e32 v74, s57, v15
	v_add_u32_e32 v76, s56, v20
	v_add_u32_e32 v78, s57, v17
	s_cmp_lg_u32 s17, 0
	v_mad_u64_u32 v[48:49], s[56:57], v48, s35, v[4:5]
	v_mad_u64_u32 v[50:51], s[56:57], v50, s35, v[4:5]
	v_mad_u64_u32 v[52:53], s[56:57], v52, s35, v[4:5]
	v_mad_u64_u32 v[54:55], s[56:57], v54, s35, v[4:5]
	v_mad_u64_u32 v[56:57], s[56:57], v56, s35, v[4:5]
	v_mad_u64_u32 v[58:59], s[56:57], v58, s35, v[4:5]
	v_mad_u64_u32 v[60:61], s[56:57], v60, s35, v[4:5]
	v_mad_u64_u32 v[62:63], s[56:57], v62, s35, v[4:5]
	v_mad_u64_u32 v[64:65], s[56:57], v64, s35, v[4:5]
	v_mad_u64_u32 v[66:67], s[56:57], v66, s35, v[4:5]
	v_mad_u64_u32 v[68:69], s[56:57], v68, s35, v[4:5]
	v_mad_u64_u32 v[70:71], s[56:57], v70, s35, v[4:5]
	v_mad_u64_u32 v[72:73], s[56:57], v72, s35, v[4:5]
	v_mad_u64_u32 v[74:75], s[56:57], v74, s35, v[4:5]
	v_mad_u64_u32 v[76:77], s[56:57], v76, s35, v[4:5]
	v_mad_u64_u32 v[78:79], s[56:57], v78, s35, v[4:5]
	s_waitcnt vmcnt(15)
	ds_write_b32 v48, v37
	s_waitcnt vmcnt(14)
	ds_write_b32 v50, v40
	s_waitcnt vmcnt(13)
	ds_write_b32 v52, v47
	s_waitcnt vmcnt(12)
	ds_write_b32 v54, v80
	s_waitcnt vmcnt(11)
	ds_write_b32 v56, v81
	s_waitcnt vmcnt(10)
	ds_write_b32 v58, v82
	s_waitcnt vmcnt(9)
	ds_write_b32 v60, v83
	s_waitcnt vmcnt(8)
	ds_write_b32 v62, v84
	s_waitcnt vmcnt(7)
	ds_write_b32 v64, v85
	s_waitcnt vmcnt(6)
	ds_write_b32 v66, v86
	s_waitcnt vmcnt(5)
	ds_write_b32 v68, v87
	s_waitcnt vmcnt(4)
	ds_write_b32 v70, v88
	s_waitcnt vmcnt(3)
	ds_write_b32 v72, v89
	s_waitcnt vmcnt(2)
	ds_write_b32 v74, v90
	s_waitcnt vmcnt(1)
	ds_write_b32 v76, v91
	s_waitcnt vmcnt(0)
	ds_write_b32 v78, v92
	s_cbranch_scc1 .LBB0_62
	s_waitcnt lgkmcnt(0)
	s_lshl_b64 s[56:57], s[6:7], 21
	s_add_u32 s2, s29, s56
	ds_read2_b32 v[28:29], v42 offset1:8
	s_addc_u32 s7, s30, s57
	s_ashr_i32 s17, s16, 31
	ds_read2_b32 v[32:33], v42 offset0:33 offset1:41
	s_lshl_b64 s[16:17], s[16:17], 1
	s_add_u32 s16, s2, s16
	ds_read2_b32 v[34:35], v42 offset0:66 offset1:74
	s_addc_u32 s17, s7, s17
	v_lshlrev_b32_e32 v2, 1, v6
	ds_read2_b32 v[36:37], v42 offset0:99 offset1:107
	v_lshl_add_u64 v[30:31], s[16:17], 0, v[2:3]
	s_waitcnt lgkmcnt(3)
	v_bfe_u32 v2, v28, 16, 1
	v_add3_u32 v2, v28, v2, s37
	s_waitcnt lgkmcnt(2)
	v_bfe_u32 v19, v32, 16, 1
	ds_read2_b32 v[48:49], v42 offset0:132 offset1:140
	v_lshrrev_b32_e32 v2, 16, v2
	v_add3_u32 v19, v32, v19, s37
	ds_read2_b32 v[50:51], v42 offset0:165 offset1:173
	v_and_or_b32 v24, v19, s38, v2
	s_waitcnt lgkmcnt(3)
	v_bfe_u32 v2, v34, 16, 1
	v_add3_u32 v2, v34, v2, s37
	s_waitcnt lgkmcnt(2)
	v_bfe_u32 v19, v36, 16, 1
	ds_read2_b32 v[52:53], v42 offset0:198 offset1:206
	v_lshrrev_b32_e32 v2, 16, v2
	v_add3_u32 v19, v36, v19, s37
	ds_read2_b32 v[54:55], v42 offset0:231 offset1:239
	v_and_or_b32 v25, v19, s38, v2
	s_waitcnt lgkmcnt(3)
	v_bfe_u32 v2, v48, 16, 1
	v_add3_u32 v2, v48, v2, s37
	s_waitcnt lgkmcnt(2)
	v_bfe_u32 v19, v50, 16, 1
	v_lshrrev_b32_e32 v2, 16, v2
	v_add3_u32 v19, v50, v19, s37
	v_and_or_b32 v26, v19, s38, v2
	s_waitcnt lgkmcnt(1)
	v_bfe_u32 v2, v52, 16, 1
	v_add3_u32 v2, v52, v2, s37
	s_waitcnt lgkmcnt(0)
	v_bfe_u32 v19, v54, 16, 1
	v_lshrrev_b32_e32 v2, 16, v2
	v_add3_u32 v19, v54, v19, s37
	v_add_u32_e32 v56, s8, v41
	v_and_or_b32 v27, v19, s38, v2
	v_ashrrev_i32_e32 v57, 31, v56
	v_bfe_u32 v2, v29, 16, 1
	v_lshlrev_b64 v[56:57], 10, v[56:57]
	v_add3_u32 v2, v29, v2, s37
	v_bfe_u32 v19, v33, 16, 1
	v_lshl_add_u64 v[56:57], v[30:31], 0, v[56:57]
	v_lshrrev_b32_e32 v2, 16, v2
	v_add3_u32 v19, v33, v19, s37
	global_store_dwordx4 v[56:57], v[24:27], off nt
	v_add_u32_e32 v28, s8, v43
	v_ashrrev_i32_e32 v29, 31, v28
	v_and_or_b32 v24, v19, s38, v2
	v_bfe_u32 v2, v35, 16, 1
	v_add3_u32 v2, v35, v2, s37
	v_bfe_u32 v19, v37, 16, 1
	v_lshrrev_b32_e32 v2, 16, v2
	v_add3_u32 v19, v37, v19, s37
	v_and_or_b32 v25, v19, s38, v2
	v_bfe_u32 v2, v49, 16, 1
	v_add3_u32 v2, v49, v2, s37
	v_bfe_u32 v19, v51, 16, 1
	v_lshrrev_b32_e32 v2, 16, v2
	v_add3_u32 v19, v51, v19, s37
	v_and_or_b32 v26, v19, s38, v2
	v_bfe_u32 v2, v53, 16, 1
	v_add3_u32 v2, v53, v2, s37
	v_bfe_u32 v19, v55, 16, 1
	v_lshrrev_b32_e32 v2, 16, v2
	v_add3_u32 v19, v55, v19, s37
	v_lshlrev_b64 v[28:29], 10, v[28:29]
	v_and_or_b32 v27, v19, s38, v2
	ds_read2_b32 v[32:33], v42 offset0:16 offset1:24
	v_lshl_add_u64 v[28:29], v[30:31], 0, v[28:29]
	global_store_dwordx4 v[28:29], v[24:27], off nt
	ds_read2_b32 v[28:29], v42 offset0:49 offset1:57
	ds_read2_b32 v[34:35], v42 offset0:82 offset1:90
	ds_read2_b32 v[36:37], v42 offset0:115 offset1:123
	s_waitcnt lgkmcnt(3)
	v_bfe_u32 v2, v32, 16, 1
	v_add3_u32 v2, v32, v2, s37
	s_waitcnt lgkmcnt(2)
	v_bfe_u32 v19, v28, 16, 1
	ds_read2_b32 v[48:49], v42 offset0:148 offset1:156
	v_lshrrev_b32_e32 v2, 16, v2
	v_add3_u32 v19, v28, v19, s37
	ds_read2_b32 v[50:51], v42 offset0:181 offset1:189
	v_and_or_b32 v24, v19, s38, v2
	s_waitcnt lgkmcnt(3)
	v_bfe_u32 v2, v34, 16, 1
	v_add3_u32 v2, v34, v2, s37
	s_waitcnt lgkmcnt(2)
	v_bfe_u32 v19, v36, 16, 1
	ds_read2_b32 v[52:53], v42 offset0:214 offset1:222
	v_lshrrev_b32_e32 v2, 16, v2
	v_add3_u32 v19, v36, v19, s37
	ds_read2_b32 v[54:55], v42 offset0:247 offset1:255
	v_and_or_b32 v25, v19, s38, v2
	s_waitcnt lgkmcnt(3)
	v_bfe_u32 v2, v48, 16, 1
	v_add3_u32 v2, v48, v2, s37
	s_waitcnt lgkmcnt(2)
	v_bfe_u32 v19, v50, 16, 1
	v_lshrrev_b32_e32 v2, 16, v2
	v_add3_u32 v19, v50, v19, s37
	v_and_or_b32 v26, v19, s38, v2
	s_waitcnt lgkmcnt(1)
	v_bfe_u32 v2, v52, 16, 1
	v_add3_u32 v2, v52, v2, s37
	s_waitcnt lgkmcnt(0)
	v_bfe_u32 v19, v54, 16, 1
	v_lshrrev_b32_e32 v2, 16, v2
	v_add3_u32 v19, v54, v19, s37
	v_add_u32_e32 v56, s8, v44
	v_and_or_b32 v27, v19, s38, v2
	v_ashrrev_i32_e32 v57, 31, v56
	v_bfe_u32 v19, v33, 16, 1
	v_lshlrev_b64 v[56:57], 10, v[56:57]
	v_bfe_u32 v2, v29, 16, 1
	v_add3_u32 v19, v33, v19, s37
	v_lshl_add_u64 v[56:57], v[30:31], 0, v[56:57]
	v_add3_u32 v2, v29, v2, s37
	v_lshrrev_b32_e32 v19, 16, v19
	global_store_dwordx4 v[56:57], v[24:27], off nt
	v_add_u32_e32 v28, s8, v45
	v_ashrrev_i32_e32 v29, 31, v28
	v_and_or_b32 v24, v2, s38, v19
	v_bfe_u32 v19, v35, 16, 1
	v_bfe_u32 v2, v37, 16, 1
	v_add3_u32 v19, v35, v19, s37
	v_add3_u32 v2, v37, v2, s37
	v_lshrrev_b32_e32 v19, 16, v19
	v_and_or_b32 v25, v2, s38, v19
	v_bfe_u32 v19, v49, 16, 1
	v_bfe_u32 v2, v51, 16, 1
	v_add3_u32 v19, v49, v19, s37
	v_add3_u32 v2, v51, v2, s37
	v_lshrrev_b32_e32 v19, 16, v19
	v_and_or_b32 v26, v2, s38, v19
	v_bfe_u32 v19, v53, 16, 1
	v_bfe_u32 v2, v55, 16, 1
	v_add3_u32 v19, v53, v19, s37
	v_add3_u32 v2, v55, v2, s37
	v_lshrrev_b32_e32 v19, 16, v19
	v_lshlrev_b64 v[28:29], 10, v[28:29]
	v_and_or_b32 v27, v2, s38, v19
	v_lshl_add_u64 v[28:29], v[30:31], 0, v[28:29]
	global_store_dwordx4 v[28:29], v[24:27], off nt
	s_waitcnt lgkmcnt(0)

.LBB0_67:
	s_lshl_b32 s17, s7, 1
	s_lshl_b32 s55, s2, 1
	v_add_u32_e32 v37, s17, v2
	v_add_u32_e32 v40, s55, v19
	v_add_u32_e32 v47, s17, v26
	v_add_u32_e32 v54, s55, v21
	v_add_u32_e32 v56, s17, v28
	v_add_u32_e32 v58, s55, v23
	v_add_u32_e32 v60, s17, v30
	v_add_u32_e32 v62, s55, v27
	v_add_u32_e32 v64, s17, v32
	v_add_u32_e32 v66, s55, v29
	v_add_u32_e32 v68, s17, v34
	v_add_u32_e32 v70, s55, v31
	v_add_u32_e32 v72, s17, v36
	v_add_u32_e32 v74, s55, v33
	v_add_u32_e32 v76, s17, v38
	v_add_u32_e32 v78, s55, v35
	v_mad_i64_i32 v[48:49], s[56:57], v37, s53, v[24:25]
	v_mad_i64_i32 v[50:51], s[56:57], v40, s53, v[24:25]
	v_mad_i64_i32 v[52:53], s[56:57], v47, s53, v[24:25]
	v_mad_i64_i32 v[54:55], s[56:57], v54, s53, v[24:25]
	v_mad_i64_i32 v[56:57], s[56:57], v56, s53, v[24:25]
	v_mad_i64_i32 v[58:59], s[56:57], v58, s53, v[24:25]
	v_mad_i64_i32 v[60:61], s[56:57], v60, s53, v[24:25]
	v_mad_i64_i32 v[62:63], s[56:57], v62, s53, v[24:25]
	v_mad_i64_i32 v[64:65], s[56:57], v64, s53, v[24:25]
	v_mad_i64_i32 v[66:67], s[56:57], v66, s53, v[24:25]
	v_mad_i64_i32 v[68:69], s[56:57], v68, s53, v[24:25]
	v_mad_i64_i32 v[70:71], s[56:57], v70, s53, v[24:25]
	v_mad_i64_i32 v[72:73], s[56:57], v72, s53, v[24:25]
	v_mad_i64_i32 v[74:75], s[56:57], v74, s53, v[24:25]
	v_mad_i64_i32 v[76:77], s[56:57], v76, s53, v[24:25]
	v_mad_i64_i32 v[78:79], s[56:57], v78, s53, v[24:25]
	global_load_dword v37, v[48:49], off nt
	global_load_dword v40, v[50:51], off nt
	global_load_dword v47, v[52:53], off nt
	global_load_dword v80, v[54:55], off nt
	global_load_dword v81, v[56:57], off nt
	global_load_dword v82, v[58:59], off nt
	global_load_dword v83, v[60:61], off nt
	global_load_dword v84, v[62:63], off nt
	global_load_dword v85, v[64:65], off nt
	global_load_dword v86, v[66:67], off nt
	global_load_dword v87, v[68:69], off nt
	global_load_dword v88, v[70:71], off nt
	global_load_dword v89, v[72:73], off nt
	global_load_dword v90, v[74:75], off nt
	global_load_dword v91, v[76:77], off nt
	global_load_dword v92, v[78:79], off nt
	s_add_i32 s7, s7, 16
	s_add_i32 s2, s2, 16
	s_add_i32 s9, s9, -16
	v_add_u32_e32 v48, s17, v0
	v_add_u32_e32 v50, s55, v1
	v_add_u32_e32 v52, s17, v8
	v_add_u32_e32 v54, s55, v5
	v_add_u32_e32 v56, s17, v10
	v_add_u32_e32 v58, s55, v7
	v_add_u32_e32 v60, s17, v12
	v_add_u32_e32 v62, s55, v9
	v_add_u32_e32 v64, s17, v14
	v_add_u32_e32 v66, s55, v11
	v_add_u32_e32 v68, s17, v16
	v_add_u32_e32 v70, s55, v13
	v_add_u32_e32 v72, s17, v18
	v_add_u32_e32 v74, s55, v15
	v_add_u32_e32 v76, s17, v20
	v_add_u32_e32 v78, s55, v17
	s_cmp_lg_u32 s9, 0
	v_mad_u64_u32 v[48:49], s[56:57], v48, s35, v[4:5]
	v_mad_u64_u32 v[50:51], s[56:57], v50, s35, v[4:5]
	v_mad_u64_u32 v[52:53], s[56:57], v52, s35, v[4:5]
	v_mad_u64_u32 v[54:55], s[56:57], v54, s35, v[4:5]
	v_mad_u64_u32 v[56:57], s[56:57], v56, s35, v[4:5]
	v_mad_u64_u32 v[58:59], s[56:57], v58, s35, v[4:5]
	v_mad_u64_u32 v[60:61], s[56:57], v60, s35, v[4:5]
	v_mad_u64_u32 v[62:63], s[56:57], v62, s35, v[4:5]
	v_mad_u64_u32 v[64:65], s[56:57], v64, s35, v[4:5]
	v_mad_u64_u32 v[66:67], s[56:57], v66, s35, v[4:5]
	v_mad_u64_u32 v[68:69], s[56:57], v68, s35, v[4:5]
	v_mad_u64_u32 v[70:71], s[56:57], v70, s35, v[4:5]
	v_mad_u64_u32 v[72:73], s[56:57], v72, s35, v[4:5]
	v_mad_u64_u32 v[74:75], s[56:57], v74, s35, v[4:5]
	v_mad_u64_u32 v[76:77], s[56:57], v76, s35, v[4:5]
	v_mad_u64_u32 v[78:79], s[56:57], v78, s35, v[4:5]
	s_waitcnt vmcnt(15)
	ds_write_b32 v48, v37
	s_waitcnt vmcnt(14)
	ds_write_b32 v50, v40
	s_waitcnt vmcnt(13)
	ds_write_b32 v52, v47
	s_waitcnt vmcnt(12)
	ds_write_b32 v54, v80
	s_waitcnt vmcnt(11)
	ds_write_b32 v56, v81
	s_waitcnt vmcnt(10)
	ds_write_b32 v58, v82
	s_waitcnt vmcnt(9)
	ds_write_b32 v60, v83
	s_waitcnt vmcnt(8)
	ds_write_b32 v62, v84
	s_waitcnt vmcnt(7)
	ds_write_b32 v64, v85
	s_waitcnt vmcnt(6)
	ds_write_b32 v66, v86
	s_waitcnt vmcnt(5)
	ds_write_b32 v68, v87
	s_waitcnt vmcnt(4)
	ds_write_b32 v70, v88
	s_waitcnt vmcnt(3)
	ds_write_b32 v72, v89
	s_waitcnt vmcnt(2)
	ds_write_b32 v74, v90
	s_waitcnt vmcnt(1)
	ds_write_b32 v76, v91
	s_waitcnt vmcnt(0)
	ds_write_b32 v78, v92
	s_cbranch_scc1 .LBB0_67
	s_waitcnt lgkmcnt(0)
	s_mul_hi_i32 s2, s6, 0xf00000
	s_mul_i32 s6, s6, 0xf00000
	s_add_u32 s9, s31, s6
	ds_read2_b32 v[28:29], v42 offset1:8
	s_addc_u32 s2, s34, s2
	s_ashr_i32 s17, s16, 31
	ds_read2_b32 v[32:33], v42 offset0:33 offset1:41
	s_lshl_b64 s[6:7], s[16:17], 1
	s_add_u32 s6, s9, s6
	ds_read2_b32 v[34:35], v42 offset0:66 offset1:74
	s_addc_u32 s7, s2, s7
	v_lshlrev_b32_e32 v2, 1, v6
	ds_read2_b32 v[36:37], v42 offset0:99 offset1:107
	v_lshl_add_u64 v[30:31], s[6:7], 0, v[2:3]
	s_waitcnt lgkmcnt(3)
	v_bfe_u32 v2, v28, 16, 1
	v_add3_u32 v2, v28, v2, s37
	s_waitcnt lgkmcnt(2)
	v_bfe_u32 v19, v32, 16, 1
	ds_read2_b32 v[48:49], v42 offset0:132 offset1:140
	v_lshrrev_b32_e32 v2, 16, v2
	v_add3_u32 v19, v32, v19, s37
	ds_read2_b32 v[50:51], v42 offset0:165 offset1:173
	v_and_or_b32 v24, v19, s38, v2
	s_waitcnt lgkmcnt(3)
	v_bfe_u32 v2, v34, 16, 1
	v_add3_u32 v2, v34, v2, s37
	s_waitcnt lgkmcnt(2)
	v_bfe_u32 v19, v36, 16, 1
	ds_read2_b32 v[52:53], v42 offset0:198 offset1:206
	v_lshrrev_b32_e32 v2, 16, v2
	v_add3_u32 v19, v36, v19, s37
	ds_read2_b32 v[54:55], v42 offset0:231 offset1:239
	v_and_or_b32 v25, v19, s38, v2
	s_waitcnt lgkmcnt(3)
	v_bfe_u32 v2, v48, 16, 1
	v_add3_u32 v2, v48, v2, s37
	s_waitcnt lgkmcnt(2)
	v_bfe_u32 v19, v50, 16, 1
	v_lshrrev_b32_e32 v2, 16, v2
	v_add3_u32 v19, v50, v19, s37
	v_and_or_b32 v26, v19, s38, v2
	s_waitcnt lgkmcnt(1)
	v_bfe_u32 v2, v52, 16, 1
	v_add3_u32 v2, v52, v2, s37
	s_waitcnt lgkmcnt(0)
	v_bfe_u32 v19, v54, 16, 1
	v_lshrrev_b32_e32 v2, 16, v2
	v_add3_u32 v19, v54, v19, s37
	v_add_u32_e32 v56, s8, v41
	v_and_or_b32 v27, v19, s38, v2
	v_ashrrev_i32_e32 v57, 31, v56
	v_bfe_u32 v2, v29, 16, 1
	v_lshlrev_b64 v[56:57], 12, v[56:57]
	v_add3_u32 v2, v29, v2, s37
	v_bfe_u32 v19, v33, 16, 1
	v_lshl_add_u64 v[56:57], v[30:31], 0, v[56:57]
	v_lshrrev_b32_e32 v2, 16, v2
	v_add3_u32 v19, v33, v19, s37
	global_store_dwordx4 v[56:57], v[24:27], off nt
	v_add_u32_e32 v28, s8, v43
	v_ashrrev_i32_e32 v29, 31, v28
	v_and_or_b32 v24, v19, s38, v2
	v_bfe_u32 v2, v35, 16, 1
	v_add3_u32 v2, v35, v2, s37
	v_bfe_u32 v19, v37, 16, 1
	v_lshrrev_b32_e32 v2, 16, v2
	v_add3_u32 v19, v37, v19, s37
	v_and_or_b32 v25, v19, s38, v2
	v_bfe_u32 v2, v49, 16, 1
	v_add3_u32 v2, v49, v2, s37
	v_bfe_u32 v19, v51, 16, 1
	v_lshrrev_b32_e32 v2, 16, v2
	v_add3_u32 v19, v51, v19, s37
	v_and_or_b32 v26, v19, s38, v2
	v_bfe_u32 v2, v53, 16, 1
	v_add3_u32 v2, v53, v2, s37
	v_bfe_u32 v19, v55, 16, 1
	v_lshrrev_b32_e32 v2, 16, v2
	v_add3_u32 v19, v55, v19, s37
	v_lshlrev_b64 v[28:29], 12, v[28:29]
	v_and_or_b32 v27, v19, s38, v2
	ds_read2_b32 v[32:33], v42 offset0:16 offset1:24
	v_lshl_add_u64 v[28:29], v[30:31], 0, v[28:29]
	global_store_dwordx4 v[28:29], v[24:27], off nt
	ds_read2_b32 v[28:29], v42 offset0:49 offset1:57
	ds_read2_b32 v[34:35], v42 offset0:82 offset1:90
	ds_read2_b32 v[36:37], v42 offset0:115 offset1:123
	s_waitcnt lgkmcnt(3)
	v_bfe_u32 v2, v32, 16, 1
	v_add3_u32 v2, v32, v2, s37
	s_waitcnt lgkmcnt(2)
	v_bfe_u32 v19, v28, 16, 1
	ds_read2_b32 v[48:49], v42 offset0:148 offset1:156
	v_lshrrev_b32_e32 v2, 16, v2
	v_add3_u32 v19, v28, v19, s37
	ds_read2_b32 v[50:51], v42 offset0:181 offset1:189
	v_and_or_b32 v24, v19, s38, v2
	s_waitcnt lgkmcnt(3)
	v_bfe_u32 v2, v34, 16, 1
	v_add3_u32 v2, v34, v2, s37
	s_waitcnt lgkmcnt(2)
	v_bfe_u32 v19, v36, 16, 1
	ds_read2_b32 v[52:53], v42 offset0:214 offset1:222
	v_lshrrev_b32_e32 v2, 16, v2
	v_add3_u32 v19, v36, v19, s37
	ds_read2_b32 v[54:55], v42 offset0:247 offset1:255
	v_and_or_b32 v25, v19, s38, v2
	s_waitcnt lgkmcnt(3)
	v_bfe_u32 v2, v48, 16, 1
	v_add3_u32 v2, v48, v2, s37
	s_waitcnt lgkmcnt(2)
	v_bfe_u32 v19, v50, 16, 1
	v_lshrrev_b32_e32 v2, 16, v2
	v_add3_u32 v19, v50, v19, s37
	v_and_or_b32 v26, v19, s38, v2
	s_waitcnt lgkmcnt(1)
	v_bfe_u32 v2, v52, 16, 1
	v_add3_u32 v2, v52, v2, s37
	s_waitcnt lgkmcnt(0)
	v_bfe_u32 v19, v54, 16, 1
	v_lshrrev_b32_e32 v2, 16, v2
	v_add3_u32 v19, v54, v19, s37
	v_add_u32_e32 v56, s8, v44
	v_and_or_b32 v27, v19, s38, v2
	v_ashrrev_i32_e32 v57, 31, v56
	v_bfe_u32 v19, v33, 16, 1
	v_lshlrev_b64 v[56:57], 12, v[56:57]
	v_bfe_u32 v2, v29, 16, 1
	v_add3_u32 v19, v33, v19, s37
	v_lshl_add_u64 v[56:57], v[30:31], 0, v[56:57]
	v_add3_u32 v2, v29, v2, s37
	v_lshrrev_b32_e32 v19, 16, v19
	global_store_dwordx4 v[56:57], v[24:27], off nt
	v_add_u32_e32 v28, s8, v45
	v_ashrrev_i32_e32 v29, 31, v28
	v_and_or_b32 v24, v2, s38, v19
	v_bfe_u32 v19, v35, 16, 1
	v_bfe_u32 v2, v37, 16, 1
	v_add3_u32 v19, v35, v19, s37
	v_add3_u32 v2, v37, v2, s37
	v_lshrrev_b32_e32 v19, 16, v19
	v_and_or_b32 v25, v2, s38, v19
	v_bfe_u32 v19, v49, 16, 1
	v_bfe_u32 v2, v51, 16, 1
	v_add3_u32 v19, v49, v19, s37
	v_add3_u32 v2, v51, v2, s37
	v_lshrrev_b32_e32 v19, 16, v19
	v_and_or_b32 v26, v2, s38, v19
	v_bfe_u32 v19, v53, 16, 1
	v_bfe_u32 v2, v55, 16, 1
	v_add3_u32 v19, v53, v19, s37
	v_add3_u32 v2, v55, v2, s37
	v_lshrrev_b32_e32 v19, 16, v19
	v_lshlrev_b64 v[28:29], 12, v[28:29]
	v_and_or_b32 v27, v2, s38, v19
	v_lshl_add_u64 v[28:29], v[30:31], 0, v[28:29]
	global_store_dwordx4 v[28:29], v[24:27], off nt
	s_waitcnt lgkmcnt(0)
	s_branch .LBB0_15

.LBB0_71:
	v_mul_hi_i32 v6, v5, s2
	v_lshrrev_b32_e32 v7, 31, v6
	v_ashrrev_i32_e32 v6, 13, v6
	v_add_u32_e32 v6, v6, v7
	v_mul_i32_i24_e32 v7, 0xc000, v6
	v_mul_i32_i24_e32 v6, 0xf00, v6
	v_sub_u32_e32 v8, v5, v7
	v_ashrrev_i32_e32 v7, 31, v6
	v_lshlrev_b64 v[6:7], 12, v[6:7]
	v_add_u32_e32 v5, s16, v5
	v_ashrrev_i32_e32 v9, 31, v8
	s_waitcnt lgkmcnt(0)
	v_lshl_add_u64 v[6:7], s[14:15], 0, v[6:7]
	v_cmp_lt_i32_e32 vcc, s8, v5
	v_lshl_add_u64 v[6:7], v[8:9], 4, v[6:7]
	s_or_b64 s[6:7], vcc, s[6:7]
	v_add_co_u32_e32 v6, vcc, 0x1040000, v6
	s_nop 1
	v_addc_co_u32_e32 v7, vcc, 0, v7, vcc
	global_store_dwordx4 v[6:7], v[0:3], off nt
	s_andn2_b64 exec, exec, s[6:7]
	s_cbranch_execnz .LBB0_71

.LBB0_74:
	s_or_b64 exec, exec, s[18:19]
	v_lshlrev_b64 v[8:9], 19, v[8:9]
	v_ashrrev_i32_e32 v11, 31, v10
	v_lshl_add_u64 v[8:9], s[6:7], 0, v[8:9]
	v_lshlrev_b64 v[10:11], 10, v[10:11]
	v_add_u32_e32 v18, s16, v18
	v_lshl_add_u64 v[8:9], v[8:9], 0, v[10:11]
	v_ashrrev_i32_e32 v13, 31, v12
	v_cmp_lt_i32_e32 vcc, s22, v18
	v_lshl_add_u64 v[8:9], v[12:13], 1, v[8:9]
	s_or_b64 s[8:9], vcc, s[8:9]
	global_store_dwordx4 v[8:9], v[0:3], off nt
	s_andn2_b64 exec, exec, s[8:9]
	s_cbranch_execz .LBB0_79

.LBB0_81:
	s_or_b64 exec, exec, s[4:5]
	v_mul_f32_e32 v19, v18, v18
	v_fmamk_f32 v20, v19, 0xb94c1982, v10
	v_fmaak_f32 v20, v19, v20, 0xbe2aaa9d
	v_mul_f32_e32 v20, v19, v20
	v_fmac_f32_e32 v18, v18, v20
	v_fmamk_f32 v20, v19, 0x37d75334, v11
	v_fmaak_f32 v20, v19, v20, 0x3d2aabf7
	v_fmaak_f32 v20, v19, v20, 0xbf000004
	v_fma_f32 v19, v19, v20, 1.0
	v_and_b32_e32 v20, 1, v17
	v_cmp_eq_u32_e32 vcc, 0, v20
	v_lshlrev_b32_e32 v17, 30, v17
	v_add_u32_e32 v4, s16, v4
	v_cndmask_b32_e64 v18, -v18, v19, vcc
	v_bitop3_b32 v17, v17, v18, s47 bitop3:0x6c
	v_cmp_class_f32_e64 vcc, v15, s48
	v_xor_b32_e32 v15, v16, v15
	v_add_u32_e32 v5, s2, v5
	v_cndmask_b32_e32 v18, v14, v17, vcc
	v_mul_f32_e32 v17, v21, v21
	v_fmamk_f32 v19, v17, 0xb94c1982, v10
	v_fmaak_f32 v19, v17, v19, 0xbe2aaa9d
	v_mul_f32_e32 v19, v17, v19
	v_fmac_f32_e32 v21, v21, v19
	v_fmamk_f32 v19, v17, 0x37d75334, v11
	v_fmaak_f32 v19, v17, v19, 0x3d2aabf7
	v_fmaak_f32 v19, v17, v19, 0xbf000004
	v_fma_f32 v17, v17, v19, 1.0
	v_and_b32_e32 v19, 1, v2
	v_lshlrev_b32_e32 v2, 30, v2
	v_cmp_eq_u32_e64 s[4:5], 0, v19
	v_and_b32_e32 v2, 0x80000000, v2
	v_xor_b32_e32 v2, v15, v2
	v_cndmask_b32_e64 v17, v17, v21, s[4:5]
	v_xor_b32_e32 v2, v2, v17
	v_cndmask_b32_e32 v19, v14, v2, vcc
	v_cmp_lt_i32_e32 vcc, s49, v4
	global_store_dwordx2 v[0:1], v[18:19], off nt
	v_lshl_add_u64 v[0:1], v[0:1], 0, s[20:21]
	s_or_b64 s[22:23], vcc, s[22:23]
	s_andn2_b64 exec, exec, s[22:23]
	s_cbranch_execz .LBB0_90

.LBB0_104:
	v_mul_hi_i32 v3, v2, s38
	s_waitcnt lgkmcnt(0)
	v_readfirstlane_b32 s4, v0
	v_lshrrev_b32_e32 v6, 31, v3
	v_ashrrev_i32_e32 v3, 5, v3
	v_readfirstlane_b32 s5, v1
	s_add_u32 s45, s4, s43
	v_add_u32_e32 v6, v3, v6
	s_addc_u32 s46, s5, s42
	v_mad_u64_u32 v[8:9], s[4:5], v6, s39, v[2:3]
	s_add_u32 s4, s45, s44
	v_ashrrev_i32_e32 v9, 31, v8
	s_addc_u32 s5, s46, 0
	v_lshlrev_b64 v[10:11], 2, v[8:9]
	v_lshl_add_u64 v[12:13], s[4:5], 0, v[10:11]
	global_load_dword v3, v[12:13], off nt
	v_add_u32_e32 v9, 0x200, v2
	v_ashrrev_i32_e32 v7, 31, v6
	v_mov_b64_e32 v[12:13], s[14:15]
	v_cmp_lt_i32_e64 s[4:5], 63, v2
	v_lshl_add_u32 v14, v6, 1, v6
	v_mov_b32_e32 v2, v9
	v_mul_i32_i24_e32 v9, 0x5556, v8
	v_lshl_add_u64 v[6:7], s[8:9], 0, v[6:7]
	v_lshrrev_b32_e32 v15, 31, v9
	v_mad_u64_u32 v[12:13], s[46:47], v6, s19, v[12:13]
	v_add_u16_sdwa v9, v9, v15 dst_sel:DWORD dst_unused:UNUSED_PAD src0_sel:WORD_1 src1_sel:DWORD
	v_mov_b32_e32 v6, v13
	s_or_b64 s[16:17], s[4:5], s[16:17]
	v_mul_lo_u16_e32 v13, 3, v9
	v_mad_u64_u32 v[6:7], s[4:5], v7, s19, v[6:7]
	v_sub_u16_e32 v7, v8, v13
	v_mov_b32_e32 v13, v6
	v_bfe_i32 v6, v7, 0, 16
	v_lshlrev_b32_sdwa v9, v21, sext(v9) dst_sel:DWORD dst_unused:UNUSED_PAD src0_sel:DWORD src1_sel:WORD_0
	v_add_lshl_u32 v6, v14, v6, 8
	v_add3_u32 v14, 0, v9, v6
	ds_read2st64_b32 v[6:7], v14 offset0:96 offset1:105
	v_lshl_add_u64 v[8:9], v[12:13], 0, v[10:11]
	ds_read2st64_b32 v[10:11], v14 offset0:114 offset1:123
	ds_read2st64_b32 v[12:13], v14 offset0:132 offset1:141
	ds_read2st64_b32 v[14:15], v14 offset0:150 offset1:159
	s_waitcnt vmcnt(0) lgkmcnt(3)
	v_add_f32_e32 v3, v3, v6
	v_add_f32_e32 v3, v3, v7
	s_waitcnt lgkmcnt(2)
	v_add_f32_e32 v3, v3, v10
	v_add_f32_e32 v3, v3, v11
	s_waitcnt lgkmcnt(1)
	v_add_f32_e32 v3, v3, v12
	v_add_f32_e32 v3, v3, v13
	s_waitcnt lgkmcnt(0)
	v_add_f32_e32 v3, v3, v14
	v_add_f32_e32 v3, v3, v15
	global_store_dword v[8:9], v3, off nt
	s_andn2_b64 exec, exec, s[16:17]
	s_cbranch_execnz .LBB0_104
	s_branch .LBB0_99
